# on top: setprio 1 before the pre-MFMA barrier, redundant wait removed
# baseline (speedup 1.0000x reference)
; #define PG8_STAGE(bufoff, gbase, voff) do { _Pragma("unroll") for (int _i = 0; _i < 2; ++_i) \
;         __builtin_amdgcn_global_load_lds((const unsigned*)((const char*)(gbase) + (voff)[_i]), (PG8_LAS unsigned*)(lds + (bufoff) + ldsw + _i * 8192), 16, 0, 0); } while (0)
; #define PG8_LDA(dst, b, h) do { _Pragma("unroll") for (int m = 0; m < 4; ++m) _Pragma("unroll") for (int k = 0; k < 2; ++k) dst[m][k] = *(const PG8_LAS bf16x8*)(lds + PG8_SA(b, h) + aoff + m * 2048 + k * 1024); } while (0)
; #define PG8_LDB(dst, b, h) do { _Pragma("unroll") for (int n = 0; n < 2; ++n) _Pragma("unroll") for (int k = 0; k < 2; ++k) dst[n][k] = *(const PG8_LAS bf16x8*)(lds + PG8_SB(b, h) + boff + n * 2048 + k * 1024); } while (0)
; #define PG8_WAIT_V(n) asm volatile("s_waitcnt vmcnt(" #n ")" ::: "memory")
; #define PG8_WAIT_L(n) asm volatile("s_waitcnt lgkmcnt(" #n ")" ::: "memory")
; #define PG8_BAR __builtin_amdgcn_s_barrier()
; #define PG8_SCHED __builtin_amdgcn_sched_barrier(0)
; template <class Epi, class Sched, bool ALIGN_EPI = false, bool SP2 = false>
; __device__ __forceinline__ void gemm_phase(PG8_LAS unsigned char* lds, const Gemm g, const Sched& S, const Epi& E) {
;     ...
;         const bool has_next = S.next(ui + 1, nxt);
;         const char* nA = has_next ? (const char*)g.A + (size_t)nxt.pm * tstep : cA; const char* nB = has_next ? (const char*)g.Bt + (size_t)nxt.pn * tstep : cB;
;         for (int t = 0; t < nt; t += 2) {
;             const bool last = (t == nt - 2);
;             const char* a1 = cA + (size_t)(t + 1) * kstep;
;             const char* a2 = last ? nA : cA + (size_t)(t + 2) * kstep; const char* b2 = last ? nB : cB + (size_t)(t + 2) * kstep;
;             const char* a3 = a2 + kstep; const char* b3 = b2 + kstep;
;             if (last && has_next) S.a_ready(nxt);
;             if constexpr (SP2) {
;             PG8_LDB(B0, 0, 0); PG8_LDB(B1, 0, 1); PG8_SCHED; PG8_LDA(At, 0, 0); PG8_STAGE(PG8_SA(1, 1), a1 + hstep, voffA);
;             PG8_WAIT_V(8); PG8_WAIT_L(0); PG8_BAR; PG8_MMA(0, 0, At, B0); PG8_MMA(0, 1, At, B1); PG8_BAR; PG8_SCHED;
;             PG8_LDA(At, 0, 1); PG8_STAGE(PG8_SB(0, 0), b2, voffB); PG8_STAGE(PG8_SB(0, 1), b2 + hstep, voffB); PG8_STAGE(PG8_SA(0, 0), a2, voffA);
;             PG8_WAIT_V(8); PG8_WAIT_L(0); PG8_BAR; PG8_MMA(1, 0, At, B0); PG8_MMA(1, 1, At, B1); PG8_BAR; PG8_SCHED;
.LBB0_132:
	s_add_u32 s18, s46, 0xfffc0080
	s_addc_u32 s38, s47, -1
	s_add_i32 s39, 0, 0x10000
	s_cmp_eq_u32 s85, 12
	s_cselect_b32 s81, s33, s38
	s_cselect_b32 s80, s73, s18
	v_add_u32_e32 v0, s39, v176
	s_cselect_b32 s45, s75, s84
	s_cselect_b32 s44, s82, s83
	s_add_i32 s18, 0, 0x14000
	ds_read_b128 v[144:147], v0
	ds_read_b128 v[148:151], v0 offset:1024
	ds_read_b128 v[152:155], v0 offset:2048
	ds_read_b128 v[156:159], v0 offset:3072
	v_add_u32_e32 v0, s18, v176
	ds_read_b128 v[160:163], v0
	ds_read_b128 v[164:167], v0 offset:1024
	ds_read_b128 v[168:171], v0 offset:2048
	ds_read_b128 v[172:175], v0 offset:3072
	v_lshl_add_u64 v[218:219], s[46:47], 0, v[140:141]
	s_add_i32 m0, s92, 0xc000
	ds_read_b128 v[180:183], v178
	ds_read_b128 v[184:187], v178 offset:1024
	ds_read_b128 v[188:191], v178 offset:2048
	ds_read_b128 v[192:195], v178 offset:3072
	ds_read_b128 v[202:205], v178 offset:4096
	ds_read_b128 v[206:209], v178 offset:5120
	ds_read_b128 v[210:213], v178 offset:6144
	ds_read_b128 v[214:217], v178 offset:7168
	global_load_lds_dwordx4 v[218:219], off
	v_lshl_add_u64 v[218:219], s[46:47], 0, v[142:143]
	s_add_i32 m0, s92, 0xe000
	s_nop 0
	global_load_lds_dwordx4 v[218:219], off
	s_waitcnt vmcnt(8)
	s_waitcnt lgkmcnt(0)
	s_setprio 1
	s_barrier
	v_mfma_f32_16x16x32_bf16 v[118:121], v[144:147], v[180:183], v[118:121]
	v_mfma_f32_16x16x32_bf16 v[118:121], v[148:151], v[184:187], v[118:121]
	v_mfma_f32_16x16x32_bf16 v[102:105], v[144:147], v[188:191], v[102:105]
	v_mfma_f32_16x16x32_bf16 v[102:105], v[148:151], v[192:195], v[102:105]
	v_mfma_f32_16x16x32_bf16 v[86:89], v[144:147], v[202:205], v[86:89]
	v_mfma_f32_16x16x32_bf16 v[86:89], v[148:151], v[206:209], v[86:89]
	v_mfma_f32_16x16x32_bf16 v[70:73], v[144:147], v[210:213], v[70:73]
	v_mfma_f32_16x16x32_bf16 v[70:73], v[148:151], v[214:217], v[70:73]
	v_mfma_f32_16x16x32_bf16 v[114:117], v[152:155], v[180:183], v[114:117]
	v_mfma_f32_16x16x32_bf16 v[114:117], v[156:159], v[184:187], v[114:117]
	v_mfma_f32_16x16x32_bf16 v[98:101], v[152:155], v[188:191], v[98:101]
	v_mfma_f32_16x16x32_bf16 v[98:101], v[156:159], v[192:195], v[98:101]
	v_mfma_f32_16x16x32_bf16 v[82:85], v[152:155], v[202:205], v[82:85]
	v_mfma_f32_16x16x32_bf16 v[82:85], v[156:159], v[206:209], v[82:85]
	v_mfma_f32_16x16x32_bf16 v[66:69], v[152:155], v[210:213], v[66:69]
	v_mfma_f32_16x16x32_bf16 v[66:69], v[156:159], v[214:217], v[66:69]
	v_mfma_f32_16x16x32_bf16 v[126:129], v[160:163], v[180:183], v[126:129]
	v_mfma_f32_16x16x32_bf16 v[126:129], v[164:167], v[184:187], v[126:129]
	v_mfma_f32_16x16x32_bf16 v[110:113], v[160:163], v[188:191], v[110:113]
	v_mfma_f32_16x16x32_bf16 v[110:113], v[164:167], v[192:195], v[110:113]
	v_mfma_f32_16x16x32_bf16 v[94:97], v[160:163], v[202:205], v[94:97]
	v_mfma_f32_16x16x32_bf16 v[94:97], v[164:167], v[206:209], v[94:97]
	v_mfma_f32_16x16x32_bf16 v[78:81], v[160:163], v[210:213], v[78:81]
	v_mfma_f32_16x16x32_bf16 v[78:81], v[164:167], v[214:217], v[78:81]
	v_mfma_f32_16x16x32_bf16 v[122:125], v[168:171], v[180:183], v[122:125]
	v_mfma_f32_16x16x32_bf16 v[122:125], v[172:175], v[184:187], v[122:125]
	v_mfma_f32_16x16x32_bf16 v[106:109], v[168:171], v[188:191], v[106:109]
	v_mfma_f32_16x16x32_bf16 v[106:109], v[172:175], v[192:195], v[106:109]
	v_mfma_f32_16x16x32_bf16 v[90:93], v[168:171], v[202:205], v[90:93]
	v_mfma_f32_16x16x32_bf16 v[90:93], v[172:175], v[206:209], v[90:93]
	v_mfma_f32_16x16x32_bf16 v[74:77], v[168:171], v[210:213], v[74:77]
	v_mfma_f32_16x16x32_bf16 v[74:77], v[172:175], v[214:217], v[74:77]
	s_setprio 0
	s_barrier
	s_add_i32 s38, s39, s91
	v_lshl_add_u64 v[218:219], s[44:45], 0, v[134:135]
	s_mov_b32 m0, s38
	ds_read_b128 v[180:183], v178 offset:16384
	ds_read_b128 v[184:187], v178 offset:17408
	ds_read_b128 v[188:191], v178 offset:18432
	ds_read_b128 v[192:195], v178 offset:19456
	ds_read_b128 v[202:205], v178 offset:20480
	ds_read_b128 v[206:209], v178 offset:21504
	ds_read_b128 v[210:213], v178 offset:22528
	ds_read_b128 v[214:217], v178 offset:23552
	global_load_lds_dwordx4 v[218:219], off
	s_add_i32 m0, s38, 0x2000
	s_add_u32 s38, s44, 0x40000
	v_lshl_add_u64 v[220:221], s[44:45], 0, v[130:131]
	s_addc_u32 s39, s45, 0
	s_add_i32 s18, s18, s91
	global_load_lds_dwordx4 v[220:221], off
	v_lshl_add_u64 v[222:223], s[38:39], 0, v[134:135]
	s_mov_b32 m0, s18
	v_lshl_add_u64 v[224:225], s[80:81], 0, v[132:133]
	global_load_lds_dwordx4 v[222:223], off
	v_lshl_add_u64 v[222:223], s[38:39], 0, v[130:131]
	s_add_i32 m0, s18, 0x2000
	s_nop 0
	global_load_lds_dwordx4 v[222:223], off
	v_lshl_add_u64 v[222:223], s[80:81], 0, v[136:137]
	s_mov_b32 m0, s92
	s_nop 0
	global_load_lds_dwordx4 v[222:223], off
	s_mov_b32 m0, s93
	s_nop 0
	global_load_lds_dwordx4 v[224:225], off
	s_waitcnt vmcnt(8)
	s_waitcnt lgkmcnt(0)
	s_setprio 1
	s_barrier
; #define PG8_STAGE(bufoff, gbase, voff) do { _Pragma("unroll") for (int _i = 0; _i < 2; ++_i) \
;         __builtin_amdgcn_global_load_lds((const unsigned*)((const char*)(gbase) + (voff)[_i]), (PG8_LAS unsigned*)(lds + (bufoff) + ldsw + _i * 8192), 16, 0, 0); } while (0)
; #define PG8_LDA(dst, b, h) do { _Pragma("unroll") for (int m = 0; m < 4; ++m) _Pragma("unroll") for (int k = 0; k < 2; ++k) dst[m][k] = *(const PG8_LAS bf16x8*)(lds + PG8_SA(b, h) + aoff + m * 2048 + k * 1024); } while (0)
; #define PG8_LDB(dst, b, h) do { _Pragma("unroll") for (int n = 0; n < 2; ++n) _Pragma("unroll") for (int k = 0; k < 2; ++k) dst[n][k] = *(const PG8_LAS bf16x8*)(lds + PG8_SB(b, h) + boff + n * 2048 + k * 1024); } while (0)
; #define PG8_MMA(ai, bj, At, Bt) do { __builtin_amdgcn_s_setprio(1); _Pragma("unroll") for (int m = 0; m < 4; ++m) _Pragma("unroll") for (int n = 0; n < 2; ++n) _Pragma("unroll") for (int k = 0; k < 2; ++k) \
;         acc[ai][bj][m][n] = __builtin_amdgcn_mfma_f32_16x16x32_bf16(Bt[n][k], At[m][k], acc[ai][bj][m][n], 0, 0, 0); __builtin_amdgcn_s_setprio(0); } while (0)
; #define PG8_WAIT_V(n) asm volatile("s_waitcnt vmcnt(" #n ")" ::: "memory")
; #define PG8_WAIT_L(n) asm volatile("s_waitcnt lgkmcnt(" #n ")" ::: "memory")
; #define PG8_BAR __builtin_amdgcn_s_barrier()
; #define PG8_SCHED __builtin_amdgcn_sched_barrier(0)
; template <class Epi, class Sched, bool ALIGN_EPI = false, bool SP2 = false>
; __device__ __forceinline__ void gemm_phase(PG8_LAS unsigned char* lds, const Gemm g, const Sched& S, const Epi& E) {
;     ...
;             PG8_WAIT_V(8); PG8_WAIT_L(0); PG8_BAR; PG8_MMA(1, 0, At, B0); PG8_MMA(1, 1, At, B1); PG8_BAR; PG8_SCHED;
;             PG8_LDB(B0, 1, 0); PG8_LDB(B1, 1, 1); PG8_SCHED; PG8_LDA(At, 1, 0); PG8_STAGE(PG8_SA(0, 1), a2 + hstep, voffA);
;             PG8_WAIT_V(8); PG8_WAIT_L(0); PG8_BAR; PG8_MMA(0, 0, At, B0); PG8_MMA(0, 1, At, B1); PG8_BAR; PG8_SCHED;
	v_mfma_f32_16x16x32_bf16 v[54:57], v[144:147], v[180:183], v[54:57]
	v_mfma_f32_16x16x32_bf16 v[54:57], v[148:151], v[184:187], v[54:57]
	v_mfma_f32_16x16x32_bf16 v[38:41], v[144:147], v[188:191], v[38:41]
	v_mfma_f32_16x16x32_bf16 v[38:41], v[148:151], v[192:195], v[38:41]
	v_mfma_f32_16x16x32_bf16 v[22:25], v[144:147], v[202:205], v[22:25]
	v_mfma_f32_16x16x32_bf16 v[22:25], v[148:151], v[206:209], v[22:25]
	v_mfma_f32_16x16x32_bf16 v[6:9], v[144:147], v[210:213], v[6:9]
	v_mfma_f32_16x16x32_bf16 v[6:9], v[148:151], v[214:217], v[6:9]
	v_mfma_f32_16x16x32_bf16 v[50:53], v[152:155], v[180:183], v[50:53]
	v_mfma_f32_16x16x32_bf16 v[50:53], v[156:159], v[184:187], v[50:53]
	v_mfma_f32_16x16x32_bf16 v[34:37], v[152:155], v[188:191], v[34:37]
	v_mfma_f32_16x16x32_bf16 v[34:37], v[156:159], v[192:195], v[34:37]
	v_mfma_f32_16x16x32_bf16 v[18:21], v[152:155], v[202:205], v[18:21]
	v_mfma_f32_16x16x32_bf16 v[18:21], v[156:159], v[206:209], v[18:21]
	v_mfma_f32_16x16x32_bf16 v[2:5], v[152:155], v[210:213], v[2:5]
	v_mfma_f32_16x16x32_bf16 v[2:5], v[156:159], v[214:217], v[2:5]
	v_mfma_f32_16x16x32_bf16 v[62:65], v[160:163], v[180:183], v[62:65]
	v_mfma_f32_16x16x32_bf16 v[62:65], v[164:167], v[184:187], v[62:65]
	v_mfma_f32_16x16x32_bf16 v[46:49], v[160:163], v[188:191], v[46:49]
	v_mfma_f32_16x16x32_bf16 v[46:49], v[164:167], v[192:195], v[46:49]
	v_mfma_f32_16x16x32_bf16 v[30:33], v[160:163], v[202:205], v[30:33]
	v_mfma_f32_16x16x32_bf16 v[30:33], v[164:167], v[206:209], v[30:33]
	v_mfma_f32_16x16x32_bf16 v[10:13], v[160:163], v[210:213], v[10:13]
	v_mfma_f32_16x16x32_bf16 v[10:13], v[164:167], v[214:217], v[10:13]
	v_mfma_f32_16x16x32_bf16 v[58:61], v[168:171], v[180:183], v[58:61]
	v_mfma_f32_16x16x32_bf16 v[58:61], v[172:175], v[184:187], v[58:61]
	v_mfma_f32_16x16x32_bf16 v[42:45], v[168:171], v[188:191], v[42:45]
	v_mfma_f32_16x16x32_bf16 v[42:45], v[172:175], v[192:195], v[42:45]
	v_mfma_f32_16x16x32_bf16 v[26:29], v[168:171], v[202:205], v[26:29]
	v_mfma_f32_16x16x32_bf16 v[26:29], v[172:175], v[206:209], v[26:29]
	v_mfma_f32_16x16x32_bf16 v[14:17], v[168:171], v[210:213], v[14:17]
	v_mfma_f32_16x16x32_bf16 v[14:17], v[172:175], v[214:217], v[14:17]
	s_setprio 0
	s_barrier
	s_add_i32 s18, 0, 0x18000
	v_add_u32_e32 v0, s18, v176
	s_add_i32 vcc_lo, 0, 0x1c000
	ds_read_b128 v[144:147], v0
	ds_read_b128 v[148:151], v0 offset:1024
	ds_read_b128 v[152:155], v0 offset:2048
	ds_read_b128 v[156:159], v0 offset:3072
	v_add_u32_e32 v0, vcc_lo, v176
	ds_read_b128 v[160:163], v0
	ds_read_b128 v[164:167], v0 offset:1024
	ds_read_b128 v[168:171], v0 offset:2048
	ds_read_b128 v[172:175], v0 offset:3072
	s_add_u32 s38, s80, 0x40000
	s_addc_u32 s39, s81, 0
	s_mov_b32 m0, s94
	v_lshl_add_u64 v[226:227], s[38:39], 0, v[136:137]
	ds_read_b128 v[180:183], v178 offset:32768
	ds_read_b128 v[184:187], v178 offset:33792
	ds_read_b128 v[188:191], v178 offset:34816
	ds_read_b128 v[192:195], v178 offset:35840
	ds_read_b128 v[202:205], v178 offset:36864
	ds_read_b128 v[206:209], v178 offset:37888
	ds_read_b128 v[210:213], v178 offset:38912
	ds_read_b128 v[214:217], v178 offset:39936
	global_load_lds_dwordx4 v[226:227], off
	v_lshl_add_u64 v[226:227], s[38:39], 0, v[132:133]
	s_mov_b32 m0, s95
	s_nop 0
	global_load_lds_dwordx4 v[226:227], off
	s_waitcnt vmcnt(8)
	s_waitcnt lgkmcnt(0)
	s_setprio 1
	s_barrier
	v_mfma_f32_16x16x32_bf16 v[118:121], v[144:147], v[180:183], v[118:121]
	v_mfma_f32_16x16x32_bf16 v[118:121], v[148:151], v[184:187], v[118:121]
	v_mfma_f32_16x16x32_bf16 v[102:105], v[144:147], v[188:191], v[102:105]
	v_mfma_f32_16x16x32_bf16 v[102:105], v[148:151], v[192:195], v[102:105]
	v_mfma_f32_16x16x32_bf16 v[86:89], v[144:147], v[202:205], v[86:89]
	v_mfma_f32_16x16x32_bf16 v[86:89], v[148:151], v[206:209], v[86:89]
	v_mfma_f32_16x16x32_bf16 v[70:73], v[144:147], v[210:213], v[70:73]
	v_mfma_f32_16x16x32_bf16 v[70:73], v[148:151], v[214:217], v[70:73]
	v_mfma_f32_16x16x32_bf16 v[114:117], v[152:155], v[180:183], v[114:117]
	v_mfma_f32_16x16x32_bf16 v[114:117], v[156:159], v[184:187], v[114:117]
	v_mfma_f32_16x16x32_bf16 v[98:101], v[152:155], v[188:191], v[98:101]
	v_mfma_f32_16x16x32_bf16 v[98:101], v[156:159], v[192:195], v[98:101]
	v_mfma_f32_16x16x32_bf16 v[82:85], v[152:155], v[202:205], v[82:85]
	v_mfma_f32_16x16x32_bf16 v[82:85], v[156:159], v[206:209], v[82:85]
	v_mfma_f32_16x16x32_bf16 v[66:69], v[152:155], v[210:213], v[66:69]
	v_mfma_f32_16x16x32_bf16 v[66:69], v[156:159], v[214:217], v[66:69]
	v_mfma_f32_16x16x32_bf16 v[126:129], v[160:163], v[180:183], v[126:129]
	v_mfma_f32_16x16x32_bf16 v[126:129], v[164:167], v[184:187], v[126:129]
	v_mfma_f32_16x16x32_bf16 v[110:113], v[160:163], v[188:191], v[110:113]
	v_mfma_f32_16x16x32_bf16 v[110:113], v[164:167], v[192:195], v[110:113]
	v_mfma_f32_16x16x32_bf16 v[94:97], v[160:163], v[202:205], v[94:97]
	v_mfma_f32_16x16x32_bf16 v[94:97], v[164:167], v[206:209], v[94:97]
	v_mfma_f32_16x16x32_bf16 v[78:81], v[160:163], v[210:213], v[78:81]
	v_mfma_f32_16x16x32_bf16 v[78:81], v[164:167], v[214:217], v[78:81]
	v_mfma_f32_16x16x32_bf16 v[122:125], v[168:171], v[180:183], v[122:125]
	v_mfma_f32_16x16x32_bf16 v[122:125], v[172:175], v[184:187], v[122:125]
	v_mfma_f32_16x16x32_bf16 v[106:109], v[168:171], v[188:191], v[106:109]
	v_mfma_f32_16x16x32_bf16 v[106:109], v[172:175], v[192:195], v[106:109]
	v_mfma_f32_16x16x32_bf16 v[90:93], v[168:171], v[202:205], v[90:93]
	v_mfma_f32_16x16x32_bf16 v[90:93], v[172:175], v[206:209], v[90:93]
	v_mfma_f32_16x16x32_bf16 v[74:77], v[168:171], v[210:213], v[74:77]
	v_mfma_f32_16x16x32_bf16 v[74:77], v[172:175], v[214:217], v[74:77]
	s_setprio 0
	s_barrier
; #define PG8_STAGE(bufoff, gbase, voff) do { _Pragma("unroll") for (int _i = 0; _i < 2; ++_i) \
;         __builtin_amdgcn_global_load_lds((const unsigned*)((const char*)(gbase) + (voff)[_i]), (PG8_LAS unsigned*)(lds + (bufoff) + ldsw + _i * 8192), 16, 0, 0); } while (0)
; #define PG8_LDA(dst, b, h) do { _Pragma("unroll") for (int m = 0; m < 4; ++m) _Pragma("unroll") for (int k = 0; k < 2; ++k) dst[m][k] = *(const PG8_LAS bf16x8*)(lds + PG8_SA(b, h) + aoff + m * 2048 + k * 1024); } while (0)
; #define PG8_WAIT_V(n) asm volatile("s_waitcnt vmcnt(" #n ")" ::: "memory")
; template <class Epi, class Sched, bool ALIGN_EPI = false, bool SP2 = false>
; __device__ __forceinline__ void gemm_phase(PG8_LAS unsigned char* lds, const Gemm g, const Sched& S, const Epi& E) {
;     ...
;             PG8_LDA(At, 1, 1); PG8_STAGE(PG8_SB(1, 0), b3, voffB); PG8_STAGE(PG8_SB(1, 1), b3 + hstep, voffB); PG8_STAGE(PG8_SA(1, 0), a3, voffA);
;             PG8_WAIT_V(8); PG8_WAIT_L(0); PG8_BAR; PG8_MMA(1, 0, At, B0); PG8_MMA(1, 1, At, B1); PG8_BAR; PG8_SCHED;
;             } else {
;             PG8_LDB(B0, 0, 0); PG8_SCHED; PG8_LDA(At, 0, 0); PG8_STAGE(PG8_SA(1, 1), a1 + hstep, voffA);
;             PG8_WAIT_L(8); PG8_BAR; PG8_WAIT_L(0); PG8_MMA(0, 0, At, B0); PG8_BAR; PG8_SCHED;
;             PG8_LDB(B1, 0, 1); PG8_STAGE(PG8_SB(0, 0), b2, voffB);
;             PG8_BAR; PG8_WAIT_L(0); PG8_MMA(0, 1, At, B1); PG8_BAR;
;             PG8_LDA(At, 0, 1); PG8_STAGE(PG8_SA(0, 0), a2, voffA);
;             PG8_BAR; PG8_WAIT_L(0); PG8_MMA(1, 0, At, B0); PG8_BAR; PG8_SCHED;
;             PG8_STAGE(PG8_SB(0, 1), b2 + hstep, voffB);
;             PG8_WAIT_V(6); PG8_BAR; PG8_MMA(1, 1, At, B1); PG8_BAR;
;             PG8_LDB(B0, 1, 0); PG8_SCHED; PG8_LDA(At, 1, 0); PG8_STAGE(PG8_SA(0, 1), a2 + hstep, voffA);
;             PG8_WAIT_L(8); PG8_BAR; PG8_WAIT_L(0); PG8_MMA(0, 0, At, B0); PG8_BAR; PG8_SCHED;
;             PG8_LDB(B1, 1, 1); PG8_STAGE(PG8_SB(1, 0), b3, voffB);
;             PG8_BAR; PG8_WAIT_L(0); PG8_MMA(0, 1, At, B1); PG8_BAR;
;             PG8_LDA(At, 1, 1); PG8_STAGE(PG8_SA(1, 0), a3, voffA);
;             PG8_BAR; PG8_WAIT_L(0); PG8_MMA(1, 0, At, B0); PG8_BAR; PG8_SCHED;
;             PG8_STAGE(PG8_SB(1, 1), b3 + hstep, voffB);
;             PG8_WAIT_V(6); PG8_BAR; PG8_MMA(1, 1, At, B1); PG8_BAR;
;             }
;         }
;         if constexpr (ALIGN_EPI) { if (wr == 0) PG8_BAR; }
	s_add_i32 s18, s18, s91
	v_lshl_add_u64 v[218:219], v[218:219], 0, s[30:31]
	s_mov_b32 m0, s18
	ds_read_b128 v[180:183], v178 offset:49152
	ds_read_b128 v[184:187], v178 offset:50176
	ds_read_b128 v[188:191], v178 offset:51200
	ds_read_b128 v[192:195], v178 offset:52224
	ds_read_b128 v[202:205], v178 offset:53248
	ds_read_b128 v[206:209], v178 offset:54272
	ds_read_b128 v[210:213], v178 offset:55296
	ds_read_b128 v[214:217], v178 offset:56320
	global_load_lds_dwordx4 v[218:219], off
	s_add_i32 m0, s18, 0x2000
	s_add_u32 s38, s44, 0x40080
	v_lshl_add_u64 v[218:219], v[220:221], 0, s[30:31]
	s_addc_u32 s39, s45, 0
	s_add_i32 s18, vcc_lo, s91
	global_load_lds_dwordx4 v[218:219], off
	v_lshl_add_u64 v[218:219], s[38:39], 0, v[134:135]
	s_mov_b32 m0, s18
	s_nop 0
	global_load_lds_dwordx4 v[218:219], off
	v_lshl_add_u64 v[218:219], s[38:39], 0, v[130:131]
	s_add_i32 m0, s18, 0x2000
	s_nop 0
	global_load_lds_dwordx4 v[218:219], off
	v_lshl_add_u64 v[218:219], v[222:223], 0, s[30:31]
	s_mov_b32 m0, s7
	s_nop 0
	global_load_lds_dwordx4 v[218:219], off
	v_lshl_add_u64 v[218:219], v[224:225], 0, s[30:31]
	s_mov_b32 m0, s96
	s_nop 0
	global_load_lds_dwordx4 v[218:219], off
	s_waitcnt vmcnt(8)
	s_waitcnt lgkmcnt(0)
	s_setprio 1
	s_barrier
	v_mfma_f32_16x16x32_bf16 v[54:57], v[144:147], v[180:183], v[54:57]
	v_mfma_f32_16x16x32_bf16 v[54:57], v[148:151], v[184:187], v[54:57]
	v_mfma_f32_16x16x32_bf16 v[38:41], v[144:147], v[188:191], v[38:41]
	v_mfma_f32_16x16x32_bf16 v[38:41], v[148:151], v[192:195], v[38:41]
	v_mfma_f32_16x16x32_bf16 v[22:25], v[144:147], v[202:205], v[22:25]
	v_mfma_f32_16x16x32_bf16 v[22:25], v[148:151], v[206:209], v[22:25]
	v_mfma_f32_16x16x32_bf16 v[6:9], v[144:147], v[210:213], v[6:9]
	v_mfma_f32_16x16x32_bf16 v[6:9], v[148:151], v[214:217], v[6:9]
	v_mfma_f32_16x16x32_bf16 v[50:53], v[152:155], v[180:183], v[50:53]
	v_mfma_f32_16x16x32_bf16 v[50:53], v[156:159], v[184:187], v[50:53]
	v_mfma_f32_16x16x32_bf16 v[34:37], v[152:155], v[188:191], v[34:37]
	v_mfma_f32_16x16x32_bf16 v[34:37], v[156:159], v[192:195], v[34:37]
	v_mfma_f32_16x16x32_bf16 v[18:21], v[152:155], v[202:205], v[18:21]
	v_mfma_f32_16x16x32_bf16 v[18:21], v[156:159], v[206:209], v[18:21]
	v_mfma_f32_16x16x32_bf16 v[2:5], v[152:155], v[210:213], v[2:5]
	v_mfma_f32_16x16x32_bf16 v[2:5], v[156:159], v[214:217], v[2:5]
	v_mfma_f32_16x16x32_bf16 v[62:65], v[160:163], v[180:183], v[62:65]
	v_mfma_f32_16x16x32_bf16 v[62:65], v[164:167], v[184:187], v[62:65]
	v_mfma_f32_16x16x32_bf16 v[46:49], v[160:163], v[188:191], v[46:49]
	v_mfma_f32_16x16x32_bf16 v[46:49], v[164:167], v[192:195], v[46:49]
	v_mfma_f32_16x16x32_bf16 v[30:33], v[160:163], v[202:205], v[30:33]
	v_mfma_f32_16x16x32_bf16 v[30:33], v[164:167], v[206:209], v[30:33]
	v_mfma_f32_16x16x32_bf16 v[10:13], v[160:163], v[210:213], v[10:13]
	v_mfma_f32_16x16x32_bf16 v[10:13], v[164:167], v[214:217], v[10:13]
	v_mfma_f32_16x16x32_bf16 v[58:61], v[168:171], v[180:183], v[58:61]
	v_mfma_f32_16x16x32_bf16 v[58:61], v[172:175], v[184:187], v[58:61]
	v_mfma_f32_16x16x32_bf16 v[42:45], v[168:171], v[188:191], v[42:45]
	v_mfma_f32_16x16x32_bf16 v[42:45], v[172:175], v[192:195], v[42:45]
	v_mfma_f32_16x16x32_bf16 v[26:29], v[168:171], v[202:205], v[26:29]
	v_mfma_f32_16x16x32_bf16 v[26:29], v[172:175], v[206:209], v[26:29]
	v_mfma_f32_16x16x32_bf16 v[14:17], v[168:171], v[210:213], v[14:17]
	v_mfma_f32_16x16x32_bf16 v[14:17], v[172:175], v[214:217], v[14:17]
	s_setprio 0
	s_barrier
	s_add_i32 s85, s85, 2
	s_add_u32 s46, s46, 0x100
	s_addc_u32 s47, s47, 0
	s_add_u32 s83, s83, 0x100
	s_addc_u32 s84, s84, 0
	s_cmp_gt_u32 s85, 13
	s_cbranch_scc0 .LBB0_132
	s_and_b64 vcc, exec, s[10:11]
	s_cbranch_vccz .LBB0_135
	s_barrier

; #define PG8_STAGE(bufoff, gbase, voff) do { _Pragma("unroll") for (int _i = 0; _i < 2; ++_i) \
;         __builtin_amdgcn_global_load_lds((const unsigned*)((const char*)(gbase) + (voff)[_i]), (PG8_LAS unsigned*)(lds + (bufoff) + ldsw + _i * 8192), 16, 0, 0); } while (0)
; #define PG8_LDA(dst, b, h) do { _Pragma("unroll") for (int m = 0; m < 4; ++m) _Pragma("unroll") for (int k = 0; k < 2; ++k) dst[m][k] = *(const PG8_LAS bf16x8*)(lds + PG8_SA(b, h) + aoff + m * 2048 + k * 1024); } while (0)
; #define PG8_LDB(dst, b, h) do { _Pragma("unroll") for (int n = 0; n < 2; ++n) _Pragma("unroll") for (int k = 0; k < 2; ++k) dst[n][k] = *(const PG8_LAS bf16x8*)(lds + PG8_SB(b, h) + boff + n * 2048 + k * 1024); } while (0)
; #define PG8_MMA(ai, bj, At, Bt) do { __builtin_amdgcn_s_setprio(1); _Pragma("unroll") for (int m = 0; m < 4; ++m) _Pragma("unroll") for (int n = 0; n < 2; ++n) _Pragma("unroll") for (int k = 0; k < 2; ++k) \
;         acc[ai][bj][m][n] = __builtin_amdgcn_mfma_f32_16x16x32_bf16(Bt[n][k], At[m][k], acc[ai][bj][m][n], 0, 0, 0); __builtin_amdgcn_s_setprio(0); } while (0)
; #define PG8_WAIT_V(n) asm volatile("s_waitcnt vmcnt(" #n ")" ::: "memory")
; #define PG8_WAIT_L(n) asm volatile("s_waitcnt lgkmcnt(" #n ")" ::: "memory")
; #define PG8_BAR __builtin_amdgcn_s_barrier()
; template <class Epi, class Sched, bool ALIGN_EPI = false, bool SP2 = false>
; __device__ __forceinline__ void gemm_phase(PG8_LAS unsigned char* lds, const Gemm g, const Sched& S, const Epi& E) {
;     ...
;             const char* a1 = cA + (size_t)(t + 1) * kstep;
;             const char* a2 = last ? nA : cA + (size_t)(t + 2) * kstep; const char* b2 = last ? nB : cB + (size_t)(t + 2) * kstep;
;             const char* a3 = a2 + kstep; const char* b3 = b2 + kstep;
;             if (last && has_next) S.a_ready(nxt);
;             if constexpr (SP2) {
;             PG8_LDB(B0, 0, 0); PG8_LDB(B1, 0, 1); PG8_SCHED; PG8_LDA(At, 0, 0); PG8_STAGE(PG8_SA(1, 1), a1 + hstep, voffA);
;             PG8_WAIT_V(8); PG8_WAIT_L(0); PG8_BAR; PG8_MMA(0, 0, At, B0); PG8_MMA(0, 1, At, B1); PG8_BAR; PG8_SCHED;
;             PG8_LDA(At, 0, 1); PG8_STAGE(PG8_SB(0, 0), b2, voffB); PG8_STAGE(PG8_SB(0, 1), b2 + hstep, voffB); PG8_STAGE(PG8_SA(0, 0), a2, voffA);
;             PG8_WAIT_V(8); PG8_WAIT_L(0); PG8_BAR; PG8_MMA(1, 0, At, B0); PG8_MMA(1, 1, At, B1); PG8_BAR; PG8_SCHED;
.LBB0_220:
	s_add_u32 s18, s60, 0xfffc0080
	s_addc_u32 s38, s61, -1
	s_add_i32 s39, 0, 0x10000
	s_cmp_eq_u32 s82, 12
	s_cselect_b32 s65, s47, s38
	s_cselect_b32 s64, s78, s18
	v_add_u32_e32 v145, s39, v141
	s_cselect_b32 s57, s49, s81
	s_cselect_b32 s56, s79, s80
	s_add_i32 s18, 0, 0x14000
	ds_read_b128 v[146:149], v145
	ds_read_b128 v[150:153], v145 offset:1024
	ds_read_b128 v[154:157], v145 offset:2048
	ds_read_b128 v[158:161], v145 offset:3072
	v_add_u32_e32 v145, s18, v141
	ds_read_b128 v[162:165], v145
	ds_read_b128 v[166:169], v145 offset:1024
	ds_read_b128 v[170:173], v145 offset:2048
	ds_read_b128 v[174:177], v145 offset:3072
	v_lshl_add_u64 v[194:195], s[60:61], 0, v[136:137]
	s_add_i32 m0, s29, 0xc000
	ds_read_b128 v[178:181], v144
	ds_read_b128 v[182:185], v144 offset:1024
	ds_read_b128 v[186:189], v144 offset:2048
	ds_read_b128 v[190:193], v144 offset:3072
	ds_read_b128 v[202:205], v144 offset:4096
	ds_read_b128 v[206:209], v144 offset:5120
	ds_read_b128 v[210:213], v144 offset:6144
	ds_read_b128 v[214:217], v144 offset:7168
	global_load_lds_dwordx4 v[194:195], off
	v_lshl_add_u64 v[194:195], s[60:61], 0, v[138:139]
	s_add_i32 m0, s29, 0xe000
	s_nop 0
	global_load_lds_dwordx4 v[194:195], off
	s_waitcnt vmcnt(8)
	s_waitcnt lgkmcnt(0)
	s_setprio 1
	s_barrier
	v_mfma_f32_16x16x32_bf16 v[114:117], v[146:149], v[178:181], v[114:117]
	v_mfma_f32_16x16x32_bf16 v[114:117], v[150:153], v[182:185], v[114:117]
	v_mfma_f32_16x16x32_bf16 v[98:101], v[146:149], v[186:189], v[98:101]
	v_mfma_f32_16x16x32_bf16 v[98:101], v[150:153], v[190:193], v[98:101]
	v_mfma_f32_16x16x32_bf16 v[82:85], v[146:149], v[202:205], v[82:85]
	v_mfma_f32_16x16x32_bf16 v[82:85], v[150:153], v[206:209], v[82:85]
	v_mfma_f32_16x16x32_bf16 v[66:69], v[146:149], v[210:213], v[66:69]
	v_mfma_f32_16x16x32_bf16 v[66:69], v[150:153], v[214:217], v[66:69]
	v_mfma_f32_16x16x32_bf16 v[118:121], v[154:157], v[178:181], v[118:121]
	v_mfma_f32_16x16x32_bf16 v[118:121], v[158:161], v[182:185], v[118:121]
	v_mfma_f32_16x16x32_bf16 v[102:105], v[154:157], v[186:189], v[102:105]
	v_mfma_f32_16x16x32_bf16 v[102:105], v[158:161], v[190:193], v[102:105]
	v_mfma_f32_16x16x32_bf16 v[86:89], v[154:157], v[202:205], v[86:89]
	v_mfma_f32_16x16x32_bf16 v[86:89], v[158:161], v[206:209], v[86:89]
	v_mfma_f32_16x16x32_bf16 v[70:73], v[154:157], v[210:213], v[70:73]
	v_mfma_f32_16x16x32_bf16 v[70:73], v[158:161], v[214:217], v[70:73]
	v_mfma_f32_16x16x32_bf16 v[122:125], v[162:165], v[178:181], v[122:125]
	v_mfma_f32_16x16x32_bf16 v[122:125], v[166:169], v[182:185], v[122:125]
	v_mfma_f32_16x16x32_bf16 v[106:109], v[162:165], v[186:189], v[106:109]
	v_mfma_f32_16x16x32_bf16 v[106:109], v[166:169], v[190:193], v[106:109]
	v_mfma_f32_16x16x32_bf16 v[90:93], v[162:165], v[202:205], v[90:93]
	v_mfma_f32_16x16x32_bf16 v[90:93], v[166:169], v[206:209], v[90:93]
	v_mfma_f32_16x16x32_bf16 v[74:77], v[162:165], v[210:213], v[74:77]
	v_mfma_f32_16x16x32_bf16 v[74:77], v[166:169], v[214:217], v[74:77]
	v_mfma_f32_16x16x32_bf16 v[126:129], v[170:173], v[178:181], v[126:129]
	v_mfma_f32_16x16x32_bf16 v[126:129], v[174:177], v[182:185], v[126:129]
	v_mfma_f32_16x16x32_bf16 v[110:113], v[170:173], v[186:189], v[110:113]
	v_mfma_f32_16x16x32_bf16 v[110:113], v[174:177], v[190:193], v[110:113]
	v_mfma_f32_16x16x32_bf16 v[94:97], v[170:173], v[202:205], v[94:97]
	v_mfma_f32_16x16x32_bf16 v[94:97], v[174:177], v[206:209], v[94:97]
	v_mfma_f32_16x16x32_bf16 v[78:81], v[170:173], v[210:213], v[78:81]
	v_mfma_f32_16x16x32_bf16 v[78:81], v[174:177], v[214:217], v[78:81]
	s_setprio 0
	s_barrier
	s_add_i32 s38, s39, s27
	v_lshl_add_u64 v[194:195], s[56:57], 0, v[0:1]
	s_mov_b32 m0, s38
	ds_read_b128 v[178:181], v144 offset:16384
	ds_read_b128 v[182:185], v144 offset:17408
	ds_read_b128 v[186:189], v144 offset:18432
	ds_read_b128 v[190:193], v144 offset:19456
	ds_read_b128 v[202:205], v144 offset:20480
	ds_read_b128 v[206:209], v144 offset:21504
	ds_read_b128 v[210:213], v144 offset:22528
	ds_read_b128 v[214:217], v144 offset:23552
	global_load_lds_dwordx4 v[194:195], off
	s_add_i32 m0, s38, 0x2000
	s_add_u32 s38, s56, 0x40000
	v_lshl_add_u64 v[218:219], s[56:57], 0, v[130:131]
	s_addc_u32 s39, s57, 0
	s_add_i32 s18, s18, s27
	global_load_lds_dwordx4 v[218:219], off
	v_lshl_add_u64 v[220:221], s[38:39], 0, v[0:1]
	s_mov_b32 m0, s18
	v_lshl_add_u64 v[222:223], s[64:65], 0, v[132:133]
	global_load_lds_dwordx4 v[220:221], off
	v_lshl_add_u64 v[220:221], s[38:39], 0, v[130:131]
	s_add_i32 m0, s18, 0x2000
	s_nop 0
	global_load_lds_dwordx4 v[220:221], off
	v_lshl_add_u64 v[220:221], s[64:65], 0, v[134:135]
	s_mov_b32 m0, s29
	s_nop 0
	global_load_lds_dwordx4 v[220:221], off
	s_mov_b32 m0, s33
	s_nop 0
	global_load_lds_dwordx4 v[222:223], off
	s_waitcnt vmcnt(8)
	s_waitcnt lgkmcnt(0)
	s_setprio 1
	s_barrier
; #define PG8_STAGE(bufoff, gbase, voff) do { _Pragma("unroll") for (int _i = 0; _i < 2; ++_i) \
;         __builtin_amdgcn_global_load_lds((const unsigned*)((const char*)(gbase) + (voff)[_i]), (PG8_LAS unsigned*)(lds + (bufoff) + ldsw + _i * 8192), 16, 0, 0); } while (0)
; #define PG8_LDA(dst, b, h) do { _Pragma("unroll") for (int m = 0; m < 4; ++m) _Pragma("unroll") for (int k = 0; k < 2; ++k) dst[m][k] = *(const PG8_LAS bf16x8*)(lds + PG8_SA(b, h) + aoff + m * 2048 + k * 1024); } while (0)
; #define PG8_LDB(dst, b, h) do { _Pragma("unroll") for (int n = 0; n < 2; ++n) _Pragma("unroll") for (int k = 0; k < 2; ++k) dst[n][k] = *(const PG8_LAS bf16x8*)(lds + PG8_SB(b, h) + boff + n * 2048 + k * 1024); } while (0)
; #define PG8_MMA(ai, bj, At, Bt) do { __builtin_amdgcn_s_setprio(1); _Pragma("unroll") for (int m = 0; m < 4; ++m) _Pragma("unroll") for (int n = 0; n < 2; ++n) _Pragma("unroll") for (int k = 0; k < 2; ++k) \
;         acc[ai][bj][m][n] = __builtin_amdgcn_mfma_f32_16x16x32_bf16(Bt[n][k], At[m][k], acc[ai][bj][m][n], 0, 0, 0); __builtin_amdgcn_s_setprio(0); } while (0)
; #define PG8_WAIT_V(n) asm volatile("s_waitcnt vmcnt(" #n ")" ::: "memory")
; #define PG8_WAIT_L(n) asm volatile("s_waitcnt lgkmcnt(" #n ")" ::: "memory")
; #define PG8_BAR __builtin_amdgcn_s_barrier()
; #define PG8_SCHED __builtin_amdgcn_sched_barrier(0)
; template <class Epi, class Sched, bool ALIGN_EPI = false, bool SP2 = false>
; __device__ __forceinline__ void gemm_phase(PG8_LAS unsigned char* lds, const Gemm g, const Sched& S, const Epi& E) {
;     ...
;             PG8_WAIT_V(8); PG8_WAIT_L(0); PG8_BAR; PG8_MMA(1, 0, At, B0); PG8_MMA(1, 1, At, B1); PG8_BAR; PG8_SCHED;
;             PG8_LDB(B0, 1, 0); PG8_LDB(B1, 1, 1); PG8_SCHED; PG8_LDA(At, 1, 0); PG8_STAGE(PG8_SA(0, 1), a2 + hstep, voffA);
;             PG8_WAIT_V(8); PG8_WAIT_L(0); PG8_BAR; PG8_MMA(0, 0, At, B0); PG8_MMA(0, 1, At, B1); PG8_BAR; PG8_SCHED;
	v_mfma_f32_16x16x32_bf16 v[50:53], v[146:149], v[178:181], v[50:53]
	v_mfma_f32_16x16x32_bf16 v[50:53], v[150:153], v[182:185], v[50:53]
	v_mfma_f32_16x16x32_bf16 v[34:37], v[146:149], v[186:189], v[34:37]
	v_mfma_f32_16x16x32_bf16 v[34:37], v[150:153], v[190:193], v[34:37]
	v_mfma_f32_16x16x32_bf16 v[18:21], v[146:149], v[202:205], v[18:21]
	v_mfma_f32_16x16x32_bf16 v[18:21], v[150:153], v[206:209], v[18:21]
	v_mfma_f32_16x16x32_bf16 v[2:5], v[146:149], v[210:213], v[2:5]
	v_mfma_f32_16x16x32_bf16 v[2:5], v[150:153], v[214:217], v[2:5]
	v_mfma_f32_16x16x32_bf16 v[54:57], v[154:157], v[178:181], v[54:57]
	v_mfma_f32_16x16x32_bf16 v[54:57], v[158:161], v[182:185], v[54:57]
	v_mfma_f32_16x16x32_bf16 v[38:41], v[154:157], v[186:189], v[38:41]
	v_mfma_f32_16x16x32_bf16 v[38:41], v[158:161], v[190:193], v[38:41]
	v_mfma_f32_16x16x32_bf16 v[22:25], v[154:157], v[202:205], v[22:25]
	v_mfma_f32_16x16x32_bf16 v[22:25], v[158:161], v[206:209], v[22:25]
	v_mfma_f32_16x16x32_bf16 v[6:9], v[154:157], v[210:213], v[6:9]
	v_mfma_f32_16x16x32_bf16 v[6:9], v[158:161], v[214:217], v[6:9]
	v_mfma_f32_16x16x32_bf16 v[58:61], v[162:165], v[178:181], v[58:61]
	v_mfma_f32_16x16x32_bf16 v[58:61], v[166:169], v[182:185], v[58:61]
	v_mfma_f32_16x16x32_bf16 v[42:45], v[162:165], v[186:189], v[42:45]
	v_mfma_f32_16x16x32_bf16 v[42:45], v[166:169], v[190:193], v[42:45]
	v_mfma_f32_16x16x32_bf16 v[26:29], v[162:165], v[202:205], v[26:29]
	v_mfma_f32_16x16x32_bf16 v[26:29], v[166:169], v[206:209], v[26:29]
	v_mfma_f32_16x16x32_bf16 v[10:13], v[162:165], v[210:213], v[10:13]
	v_mfma_f32_16x16x32_bf16 v[10:13], v[166:169], v[214:217], v[10:13]
	v_mfma_f32_16x16x32_bf16 v[62:65], v[170:173], v[178:181], v[62:65]
	v_mfma_f32_16x16x32_bf16 v[62:65], v[174:177], v[182:185], v[62:65]
	v_mfma_f32_16x16x32_bf16 v[46:49], v[170:173], v[186:189], v[46:49]
	v_mfma_f32_16x16x32_bf16 v[46:49], v[174:177], v[190:193], v[46:49]
	v_mfma_f32_16x16x32_bf16 v[30:33], v[170:173], v[202:205], v[30:33]
	v_mfma_f32_16x16x32_bf16 v[30:33], v[174:177], v[206:209], v[30:33]
	v_mfma_f32_16x16x32_bf16 v[14:17], v[170:173], v[210:213], v[14:17]
	v_mfma_f32_16x16x32_bf16 v[14:17], v[174:177], v[214:217], v[14:17]
	s_setprio 0
	s_barrier
	s_add_i32 s18, 0, 0x18000
	v_add_u32_e32 v145, s18, v141
	s_add_i32 s83, 0, 0x1c000
	ds_read_b128 v[146:149], v145
	ds_read_b128 v[150:153], v145 offset:1024
	ds_read_b128 v[154:157], v145 offset:2048
	ds_read_b128 v[158:161], v145 offset:3072
	v_add_u32_e32 v145, s83, v141
	ds_read_b128 v[162:165], v145
	ds_read_b128 v[166:169], v145 offset:1024
	ds_read_b128 v[170:173], v145 offset:2048
	ds_read_b128 v[174:177], v145 offset:3072
	s_add_u32 s38, s64, 0x40000
	s_addc_u32 s39, s65, 0
	s_mov_b32 m0, s58
	v_lshl_add_u64 v[224:225], s[38:39], 0, v[134:135]
	ds_read_b128 v[178:181], v144 offset:32768
	ds_read_b128 v[182:185], v144 offset:33792
	ds_read_b128 v[186:189], v144 offset:34816
	ds_read_b128 v[190:193], v144 offset:35840
	ds_read_b128 v[202:205], v144 offset:36864
	ds_read_b128 v[206:209], v144 offset:37888
	ds_read_b128 v[210:213], v144 offset:38912
	ds_read_b128 v[214:217], v144 offset:39936
	global_load_lds_dwordx4 v[224:225], off
	v_lshl_add_u64 v[224:225], s[38:39], 0, v[132:133]
	s_mov_b32 m0, s69
	s_nop 0
	global_load_lds_dwordx4 v[224:225], off
	s_waitcnt vmcnt(8)
	s_waitcnt lgkmcnt(0)
	s_setprio 1
	s_barrier
	v_mfma_f32_16x16x32_bf16 v[114:117], v[146:149], v[178:181], v[114:117]
	v_mfma_f32_16x16x32_bf16 v[114:117], v[150:153], v[182:185], v[114:117]
	v_mfma_f32_16x16x32_bf16 v[98:101], v[146:149], v[186:189], v[98:101]
	v_mfma_f32_16x16x32_bf16 v[98:101], v[150:153], v[190:193], v[98:101]
	v_mfma_f32_16x16x32_bf16 v[82:85], v[146:149], v[202:205], v[82:85]
	v_mfma_f32_16x16x32_bf16 v[82:85], v[150:153], v[206:209], v[82:85]
	v_mfma_f32_16x16x32_bf16 v[66:69], v[146:149], v[210:213], v[66:69]
	v_mfma_f32_16x16x32_bf16 v[66:69], v[150:153], v[214:217], v[66:69]
	v_mfma_f32_16x16x32_bf16 v[118:121], v[154:157], v[178:181], v[118:121]
	v_mfma_f32_16x16x32_bf16 v[118:121], v[158:161], v[182:185], v[118:121]
	v_mfma_f32_16x16x32_bf16 v[102:105], v[154:157], v[186:189], v[102:105]
	v_mfma_f32_16x16x32_bf16 v[102:105], v[158:161], v[190:193], v[102:105]
	v_mfma_f32_16x16x32_bf16 v[86:89], v[154:157], v[202:205], v[86:89]
	v_mfma_f32_16x16x32_bf16 v[86:89], v[158:161], v[206:209], v[86:89]
	v_mfma_f32_16x16x32_bf16 v[70:73], v[154:157], v[210:213], v[70:73]
	v_mfma_f32_16x16x32_bf16 v[70:73], v[158:161], v[214:217], v[70:73]
	v_mfma_f32_16x16x32_bf16 v[122:125], v[162:165], v[178:181], v[122:125]
	v_mfma_f32_16x16x32_bf16 v[122:125], v[166:169], v[182:185], v[122:125]
	v_mfma_f32_16x16x32_bf16 v[106:109], v[162:165], v[186:189], v[106:109]
	v_mfma_f32_16x16x32_bf16 v[106:109], v[166:169], v[190:193], v[106:109]
	v_mfma_f32_16x16x32_bf16 v[90:93], v[162:165], v[202:205], v[90:93]
	v_mfma_f32_16x16x32_bf16 v[90:93], v[166:169], v[206:209], v[90:93]
	v_mfma_f32_16x16x32_bf16 v[74:77], v[162:165], v[210:213], v[74:77]
	v_mfma_f32_16x16x32_bf16 v[74:77], v[166:169], v[214:217], v[74:77]
	v_mfma_f32_16x16x32_bf16 v[126:129], v[170:173], v[178:181], v[126:129]
	v_mfma_f32_16x16x32_bf16 v[126:129], v[174:177], v[182:185], v[126:129]
	v_mfma_f32_16x16x32_bf16 v[110:113], v[170:173], v[186:189], v[110:113]
	v_mfma_f32_16x16x32_bf16 v[110:113], v[174:177], v[190:193], v[110:113]
	v_mfma_f32_16x16x32_bf16 v[94:97], v[170:173], v[202:205], v[94:97]
	v_mfma_f32_16x16x32_bf16 v[94:97], v[174:177], v[206:209], v[94:97]
	v_mfma_f32_16x16x32_bf16 v[78:81], v[170:173], v[210:213], v[78:81]
	v_mfma_f32_16x16x32_bf16 v[78:81], v[174:177], v[214:217], v[78:81]
	s_setprio 0
	s_barrier
; #define PG8_STAGE(bufoff, gbase, voff) do { _Pragma("unroll") for (int _i = 0; _i < 2; ++_i) \
;         __builtin_amdgcn_global_load_lds((const unsigned*)((const char*)(gbase) + (voff)[_i]), (PG8_LAS unsigned*)(lds + (bufoff) + ldsw + _i * 8192), 16, 0, 0); } while (0)
; #define PG8_LDA(dst, b, h) do { _Pragma("unroll") for (int m = 0; m < 4; ++m) _Pragma("unroll") for (int k = 0; k < 2; ++k) dst[m][k] = *(const PG8_LAS bf16x8*)(lds + PG8_SA(b, h) + aoff + m * 2048 + k * 1024); } while (0)
; #define PG8_MMA(ai, bj, At, Bt) do { __builtin_amdgcn_s_setprio(1); _Pragma("unroll") for (int m = 0; m < 4; ++m) _Pragma("unroll") for (int n = 0; n < 2; ++n) _Pragma("unroll") for (int k = 0; k < 2; ++k) \
;         acc[ai][bj][m][n] = __builtin_amdgcn_mfma_f32_16x16x32_bf16(Bt[n][k], At[m][k], acc[ai][bj][m][n], 0, 0, 0); __builtin_amdgcn_s_setprio(0); } while (0)
; #define PG8_WAIT_V(n) asm volatile("s_waitcnt vmcnt(" #n ")" ::: "memory")
; #define PG8_WAIT_L(n) asm volatile("s_waitcnt lgkmcnt(" #n ")" ::: "memory")
; #define PG8_BAR __builtin_amdgcn_s_barrier()
; #define PG8_SCHED __builtin_amdgcn_sched_barrier(0)
; template <class Epi, class Sched, bool ALIGN_EPI = false, bool SP2 = false>
; __device__ __forceinline__ void gemm_phase(PG8_LAS unsigned char* lds, const Gemm g, const Sched& S, const Epi& E) {
;     ...
;             PG8_LDA(At, 1, 1); PG8_STAGE(PG8_SB(1, 0), b3, voffB); PG8_STAGE(PG8_SB(1, 1), b3 + hstep, voffB); PG8_STAGE(PG8_SA(1, 0), a3, voffA);
;             PG8_WAIT_V(8); PG8_WAIT_L(0); PG8_BAR; PG8_MMA(1, 0, At, B0); PG8_MMA(1, 1, At, B1); PG8_BAR; PG8_SCHED;
;     ...
;         if constexpr (ALIGN_EPI) { if (wr == 0) PG8_BAR; }
	s_add_i32 s18, s18, s27
	v_lshl_add_u64 v[194:195], v[194:195], 0, s[30:31]
	s_mov_b32 m0, s18
	ds_read_b128 v[178:181], v144 offset:49152
	ds_read_b128 v[182:185], v144 offset:50176
	ds_read_b128 v[186:189], v144 offset:51200
	ds_read_b128 v[190:193], v144 offset:52224
	ds_read_b128 v[202:205], v144 offset:53248
	ds_read_b128 v[206:209], v144 offset:54272
	ds_read_b128 v[210:213], v144 offset:55296
	ds_read_b128 v[214:217], v144 offset:56320
	global_load_lds_dwordx4 v[194:195], off
	s_add_i32 m0, s18, 0x2000
	s_add_u32 s38, s56, 0x40080
	v_lshl_add_u64 v[194:195], v[218:219], 0, s[30:31]
	s_addc_u32 s39, s57, 0
	s_add_i32 s18, s83, s27
	global_load_lds_dwordx4 v[194:195], off
	v_lshl_add_u64 v[194:195], s[38:39], 0, v[0:1]
	s_mov_b32 m0, s18
	s_nop 0
	global_load_lds_dwordx4 v[194:195], off
	v_lshl_add_u64 v[194:195], s[38:39], 0, v[130:131]
	s_add_i32 m0, s18, 0x2000
	s_nop 0
	global_load_lds_dwordx4 v[194:195], off
	v_lshl_add_u64 v[194:195], v[220:221], 0, s[30:31]
	s_mov_b32 m0, s71
	s_nop 0
	global_load_lds_dwordx4 v[194:195], off
	v_lshl_add_u64 v[194:195], v[222:223], 0, s[30:31]
	s_mov_b32 m0, s72
	s_nop 0
	global_load_lds_dwordx4 v[194:195], off
	s_waitcnt vmcnt(8)
	s_waitcnt lgkmcnt(0)
	s_setprio 1
	s_barrier
	v_mfma_f32_16x16x32_bf16 v[50:53], v[146:149], v[178:181], v[50:53]
	v_mfma_f32_16x16x32_bf16 v[50:53], v[150:153], v[182:185], v[50:53]
	v_mfma_f32_16x16x32_bf16 v[34:37], v[146:149], v[186:189], v[34:37]
	v_mfma_f32_16x16x32_bf16 v[34:37], v[150:153], v[190:193], v[34:37]
	v_mfma_f32_16x16x32_bf16 v[18:21], v[146:149], v[202:205], v[18:21]
	v_mfma_f32_16x16x32_bf16 v[18:21], v[150:153], v[206:209], v[18:21]
	v_mfma_f32_16x16x32_bf16 v[2:5], v[146:149], v[210:213], v[2:5]
	v_mfma_f32_16x16x32_bf16 v[2:5], v[150:153], v[214:217], v[2:5]
	v_mfma_f32_16x16x32_bf16 v[54:57], v[154:157], v[178:181], v[54:57]
	v_mfma_f32_16x16x32_bf16 v[54:57], v[158:161], v[182:185], v[54:57]
	v_mfma_f32_16x16x32_bf16 v[38:41], v[154:157], v[186:189], v[38:41]
	v_mfma_f32_16x16x32_bf16 v[38:41], v[158:161], v[190:193], v[38:41]
	v_mfma_f32_16x16x32_bf16 v[22:25], v[154:157], v[202:205], v[22:25]
	v_mfma_f32_16x16x32_bf16 v[22:25], v[158:161], v[206:209], v[22:25]
	v_mfma_f32_16x16x32_bf16 v[6:9], v[154:157], v[210:213], v[6:9]
	v_mfma_f32_16x16x32_bf16 v[6:9], v[158:161], v[214:217], v[6:9]
	v_mfma_f32_16x16x32_bf16 v[58:61], v[162:165], v[178:181], v[58:61]
	v_mfma_f32_16x16x32_bf16 v[58:61], v[166:169], v[182:185], v[58:61]
	v_mfma_f32_16x16x32_bf16 v[42:45], v[162:165], v[186:189], v[42:45]
	v_mfma_f32_16x16x32_bf16 v[42:45], v[166:169], v[190:193], v[42:45]
	v_mfma_f32_16x16x32_bf16 v[26:29], v[162:165], v[202:205], v[26:29]
	v_mfma_f32_16x16x32_bf16 v[26:29], v[166:169], v[206:209], v[26:29]
	v_mfma_f32_16x16x32_bf16 v[10:13], v[162:165], v[210:213], v[10:13]
	v_mfma_f32_16x16x32_bf16 v[10:13], v[166:169], v[214:217], v[10:13]
	v_mfma_f32_16x16x32_bf16 v[62:65], v[170:173], v[178:181], v[62:65]
	v_mfma_f32_16x16x32_bf16 v[62:65], v[174:177], v[182:185], v[62:65]
	v_mfma_f32_16x16x32_bf16 v[46:49], v[170:173], v[186:189], v[46:49]
	v_mfma_f32_16x16x32_bf16 v[46:49], v[174:177], v[190:193], v[46:49]
	v_mfma_f32_16x16x32_bf16 v[30:33], v[170:173], v[202:205], v[30:33]
	v_mfma_f32_16x16x32_bf16 v[30:33], v[174:177], v[206:209], v[30:33]
	v_mfma_f32_16x16x32_bf16 v[14:17], v[170:173], v[210:213], v[14:17]
	v_mfma_f32_16x16x32_bf16 v[14:17], v[174:177], v[214:217], v[14:17]
	s_setprio 0
	s_barrier
	s_add_i32 s82, s82, 2
	s_add_u32 s60, s60, 0x100
	s_addc_u32 s61, s61, 0
	s_add_u32 s80, s80, 0x100
	s_addc_u32 s81, s81, 0
	s_cmp_gt_u32 s82, 13
	s_cbranch_scc0 .LBB0_220
	s_and_b64 vcc, exec, s[44:45]
	s_cbranch_vccz .LBB0_223
	s_barrier

; #define PG8_STAGE(bufoff, gbase, voff) do { _Pragma("unroll") for (int _i = 0; _i < 2; ++_i) \
;         __builtin_amdgcn_global_load_lds((const unsigned*)((const char*)(gbase) + (voff)[_i]), (PG8_LAS unsigned*)(lds + (bufoff) + ldsw + _i * 8192), 16, 0, 0); } while (0)
; #define PG8_LDA(dst, b, h) do { _Pragma("unroll") for (int m = 0; m < 4; ++m) _Pragma("unroll") for (int k = 0; k < 2; ++k) dst[m][k] = *(const PG8_LAS bf16x8*)(lds + PG8_SA(b, h) + aoff + m * 2048 + k * 1024); } while (0)
; #define PG8_LDB(dst, b, h) do { _Pragma("unroll") for (int n = 0; n < 2; ++n) _Pragma("unroll") for (int k = 0; k < 2; ++k) dst[n][k] = *(const PG8_LAS bf16x8*)(lds + PG8_SB(b, h) + boff + n * 2048 + k * 1024); } while (0)
; #define PG8_MMA(ai, bj, At, Bt) do { __builtin_amdgcn_s_setprio(1); _Pragma("unroll") for (int m = 0; m < 4; ++m) _Pragma("unroll") for (int n = 0; n < 2; ++n) _Pragma("unroll") for (int k = 0; k < 2; ++k) \
;         acc[ai][bj][m][n] = __builtin_amdgcn_mfma_f32_16x16x32_bf16(Bt[n][k], At[m][k], acc[ai][bj][m][n], 0, 0, 0); __builtin_amdgcn_s_setprio(0); } while (0)
; #define PG8_WAIT_V(n) asm volatile("s_waitcnt vmcnt(" #n ")" ::: "memory")
; #define PG8_WAIT_L(n) asm volatile("s_waitcnt lgkmcnt(" #n ")" ::: "memory")
; #define PG8_BAR __builtin_amdgcn_s_barrier()
; template <class Epi, class Sched, bool ALIGN_EPI = false, bool SP2 = false>
; __device__ __forceinline__ void gemm_phase(PG8_LAS unsigned char* lds, const Gemm g, const Sched& S, const Epi& E) {
;     ...
;             const char* a1 = cA + (size_t)(t + 1) * kstep;
;             const char* a2 = last ? nA : cA + (size_t)(t + 2) * kstep; const char* b2 = last ? nB : cB + (size_t)(t + 2) * kstep;
;             const char* a3 = a2 + kstep; const char* b3 = b2 + kstep;
;             if (last && has_next) S.a_ready(nxt);
;             if constexpr (SP2) {
;             PG8_LDB(B0, 0, 0); PG8_LDB(B1, 0, 1); PG8_SCHED; PG8_LDA(At, 0, 0); PG8_STAGE(PG8_SA(1, 1), a1 + hstep, voffA);
;             PG8_WAIT_V(8); PG8_WAIT_L(0); PG8_BAR; PG8_MMA(0, 0, At, B0); PG8_MMA(0, 1, At, B1); PG8_BAR; PG8_SCHED;
;             PG8_LDA(At, 0, 1); PG8_STAGE(PG8_SB(0, 0), b2, voffB); PG8_STAGE(PG8_SB(0, 1), b2 + hstep, voffB); PG8_STAGE(PG8_SA(0, 0), a2, voffA);
;             PG8_WAIT_V(8); PG8_WAIT_L(0); PG8_BAR; PG8_MMA(1, 0, At, B0); PG8_MMA(1, 1, At, B1); PG8_BAR; PG8_SCHED;
.LBB0_274:
	s_add_i32 vcc_lo, s46, 2
	s_add_u32 s38, s48, 0x80
	s_addc_u32 s39, s49, 0
	s_add_i32 vcc_hi, 0, 0x10000
	s_cmp_eq_u32 s99, s46
	s_cselect_b32 s47, s81, s39
	s_cselect_b32 s46, s80, s38
	s_cselect_b32 s39, s83, s51
	s_cselect_b32 s38, s82, s50
	s_add_i32 s18, 0, 0x14000
	v_add_u32_e32 v142, vcc_hi, v245
	v_add_u32_e32 v158, s18, v245
	ds_read_b128 v[110:113], v142
	ds_read_b128 v[118:121], v142 offset:1024
	ds_read_b128 v[138:141], v142 offset:2048
	ds_read_b128 v[142:145], v142 offset:3072
	ds_read_b128 v[146:149], v158
	ds_read_b128 v[150:153], v158 offset:1024
	ds_read_b128 v[154:157], v158 offset:2048
	ds_read_b128 v[158:161], v158 offset:3072
	v_lshl_add_u64 v[210:211], s[48:49], 0, v[206:207]
	s_add_i32 m0, s92, 0xc000
	ds_read_b128 v[162:165], v247
	ds_read_b128 v[166:169], v247 offset:1024
	ds_read_b128 v[170:173], v247 offset:2048
	ds_read_b128 v[174:177], v247 offset:3072
	ds_read_b128 v[178:181], v247 offset:4096
	ds_read_b128 v[182:185], v247 offset:5120
	ds_read_b128 v[186:189], v247 offset:6144
	ds_read_b128 v[190:193], v247 offset:7168
	global_load_lds_dwordx4 v[210:211], off
	v_lshl_add_u64 v[210:211], s[48:49], 0, v[208:209]
	s_add_i32 m0, s92, 0xe000
	s_nop 0
	global_load_lds_dwordx4 v[210:211], off
	s_waitcnt vmcnt(8)
	s_waitcnt lgkmcnt(0)
	s_setprio 1
	s_barrier
	v_mfma_f32_16x16x32_bf16 v[130:133], v[110:113], v[162:165], v[130:133]
	v_mfma_f32_16x16x32_bf16 v[130:133], v[118:121], v[166:169], v[130:133]
	v_mfma_f32_16x16x32_bf16 v[114:117], v[110:113], v[170:173], v[114:117]
	v_mfma_f32_16x16x32_bf16 v[114:117], v[118:121], v[174:177], v[114:117]
	v_mfma_f32_16x16x32_bf16 v[94:97], v[110:113], v[178:181], v[94:97]
	v_mfma_f32_16x16x32_bf16 v[94:97], v[118:121], v[182:185], v[94:97]
	v_mfma_f32_16x16x32_bf16 v[78:81], v[110:113], v[186:189], v[78:81]
	v_mfma_f32_16x16x32_bf16 v[78:81], v[118:121], v[190:193], v[78:81]
	v_mfma_f32_16x16x32_bf16 v[134:137], v[138:141], v[162:165], v[134:137]
	v_mfma_f32_16x16x32_bf16 v[134:137], v[142:145], v[166:169], v[134:137]
	v_mfma_f32_16x16x32_bf16 v[106:109], v[138:141], v[170:173], v[106:109]
	v_mfma_f32_16x16x32_bf16 v[106:109], v[142:145], v[174:177], v[106:109]
	v_mfma_f32_16x16x32_bf16 v[90:93], v[138:141], v[178:181], v[90:93]
	v_mfma_f32_16x16x32_bf16 v[90:93], v[142:145], v[182:185], v[90:93]
	v_mfma_f32_16x16x32_bf16 v[74:77], v[138:141], v[186:189], v[74:77]
	v_mfma_f32_16x16x32_bf16 v[74:77], v[142:145], v[190:193], v[74:77]
	v_mfma_f32_16x16x32_bf16 v[126:129], v[146:149], v[162:165], v[126:129]
	v_mfma_f32_16x16x32_bf16 v[126:129], v[150:153], v[166:169], v[126:129]
	v_mfma_f32_16x16x32_bf16 v[102:105], v[146:149], v[170:173], v[102:105]
	v_mfma_f32_16x16x32_bf16 v[102:105], v[150:153], v[174:177], v[102:105]
	v_mfma_f32_16x16x32_bf16 v[86:89], v[146:149], v[178:181], v[86:89]
	v_mfma_f32_16x16x32_bf16 v[86:89], v[150:153], v[182:185], v[86:89]
	v_mfma_f32_16x16x32_bf16 v[70:73], v[146:149], v[186:189], v[70:73]
	v_mfma_f32_16x16x32_bf16 v[70:73], v[150:153], v[190:193], v[70:73]
	v_mfma_f32_16x16x32_bf16 v[122:125], v[154:157], v[162:165], v[122:125]
	v_mfma_f32_16x16x32_bf16 v[122:125], v[158:161], v[166:169], v[122:125]
	v_mfma_f32_16x16x32_bf16 v[98:101], v[154:157], v[170:173], v[98:101]
	v_mfma_f32_16x16x32_bf16 v[98:101], v[158:161], v[174:177], v[98:101]
	v_mfma_f32_16x16x32_bf16 v[82:85], v[154:157], v[178:181], v[82:85]
	v_mfma_f32_16x16x32_bf16 v[82:85], v[158:161], v[182:185], v[82:85]
	v_mfma_f32_16x16x32_bf16 v[66:69], v[154:157], v[186:189], v[66:69]
	v_mfma_f32_16x16x32_bf16 v[66:69], v[158:161], v[190:193], v[66:69]
	s_setprio 0
	s_barrier
	s_add_i32 vcc_hi, vcc_hi, s6
	v_lshl_add_u64 v[210:211], s[38:39], 0, v[0:1]
	s_mov_b32 m0, vcc_hi
	ds_read_b128 v[162:165], v247 offset:16384
	ds_read_b128 v[166:169], v247 offset:17408
	ds_read_b128 v[170:173], v247 offset:18432
	ds_read_b128 v[174:177], v247 offset:19456
	ds_read_b128 v[178:181], v247 offset:20480
	ds_read_b128 v[182:185], v247 offset:21504
	ds_read_b128 v[186:189], v247 offset:22528
	ds_read_b128 v[190:193], v247 offset:23552
	global_load_lds_dwordx4 v[210:211], off
	s_add_i32 m0, vcc_hi, 0x2000
	v_lshl_add_u64 v[212:213], s[38:39], 0, v[204:205]
	s_add_u32 s38, s38, s58
	s_addc_u32 s39, s39, 0
	s_add_i32 s18, s18, s6
	global_load_lds_dwordx4 v[212:213], off
	v_lshl_add_u64 v[214:215], s[38:39], 0, v[0:1]
	s_mov_b32 m0, s18
	v_lshl_add_u64 v[216:217], s[38:39], 0, v[204:205]
	global_load_lds_dwordx4 v[214:215], off
	s_add_i32 m0, s18, 0x2000
	v_lshl_add_u64 v[218:219], s[46:47], 0, v[194:195]
	global_load_lds_dwordx4 v[216:217], off
	s_mov_b32 m0, s92
	v_lshl_add_u64 v[220:221], s[46:47], 0, v[202:203]
	global_load_lds_dwordx4 v[218:219], off
	s_mov_b32 m0, s93
	s_nop 0
	global_load_lds_dwordx4 v[220:221], off
	s_waitcnt vmcnt(8)
	s_waitcnt lgkmcnt(0)
	s_setprio 1
	s_barrier
; #define PG8_STAGE(bufoff, gbase, voff) do { _Pragma("unroll") for (int _i = 0; _i < 2; ++_i) \
;         __builtin_amdgcn_global_load_lds((const unsigned*)((const char*)(gbase) + (voff)[_i]), (PG8_LAS unsigned*)(lds + (bufoff) + ldsw + _i * 8192), 16, 0, 0); } while (0)
; #define PG8_LDA(dst, b, h) do { _Pragma("unroll") for (int m = 0; m < 4; ++m) _Pragma("unroll") for (int k = 0; k < 2; ++k) dst[m][k] = *(const PG8_LAS bf16x8*)(lds + PG8_SA(b, h) + aoff + m * 2048 + k * 1024); } while (0)
; #define PG8_LDB(dst, b, h) do { _Pragma("unroll") for (int n = 0; n < 2; ++n) _Pragma("unroll") for (int k = 0; k < 2; ++k) dst[n][k] = *(const PG8_LAS bf16x8*)(lds + PG8_SB(b, h) + boff + n * 2048 + k * 1024); } while (0)
; #define PG8_MMA(ai, bj, At, Bt) do { __builtin_amdgcn_s_setprio(1); _Pragma("unroll") for (int m = 0; m < 4; ++m) _Pragma("unroll") for (int n = 0; n < 2; ++n) _Pragma("unroll") for (int k = 0; k < 2; ++k) \
;         acc[ai][bj][m][n] = __builtin_amdgcn_mfma_f32_16x16x32_bf16(Bt[n][k], At[m][k], acc[ai][bj][m][n], 0, 0, 0); __builtin_amdgcn_s_setprio(0); } while (0)
; #define PG8_WAIT_V(n) asm volatile("s_waitcnt vmcnt(" #n ")" ::: "memory")
; #define PG8_WAIT_L(n) asm volatile("s_waitcnt lgkmcnt(" #n ")" ::: "memory")
; #define PG8_BAR __builtin_amdgcn_s_barrier()
; #define PG8_SCHED __builtin_amdgcn_sched_barrier(0)
; template <class Epi, class Sched, bool ALIGN_EPI = false, bool SP2 = false>
; __device__ __forceinline__ void gemm_phase(PG8_LAS unsigned char* lds, const Gemm g, const Sched& S, const Epi& E) {
;     ...
;             PG8_WAIT_V(8); PG8_WAIT_L(0); PG8_BAR; PG8_MMA(1, 0, At, B0); PG8_MMA(1, 1, At, B1); PG8_BAR; PG8_SCHED;
;             PG8_LDB(B0, 1, 0); PG8_LDB(B1, 1, 1); PG8_SCHED; PG8_LDA(At, 1, 0); PG8_STAGE(PG8_SA(0, 1), a2 + hstep, voffA);
;             PG8_WAIT_V(8); PG8_WAIT_L(0); PG8_BAR; PG8_MMA(0, 0, At, B0); PG8_MMA(0, 1, At, B1); PG8_BAR; PG8_SCHED;
	v_mfma_f32_16x16x32_bf16 v[62:65], v[110:113], v[162:165], v[62:65]
	v_mfma_f32_16x16x32_bf16 v[62:65], v[118:121], v[166:169], v[62:65]
	v_mfma_f32_16x16x32_bf16 v[46:49], v[110:113], v[170:173], v[46:49]
	v_mfma_f32_16x16x32_bf16 v[46:49], v[118:121], v[174:177], v[46:49]
	v_mfma_f32_16x16x32_bf16 v[30:33], v[110:113], v[178:181], v[30:33]
	v_mfma_f32_16x16x32_bf16 v[30:33], v[118:121], v[182:185], v[30:33]
	v_mfma_f32_16x16x32_bf16 v[14:17], v[110:113], v[186:189], v[14:17]
	v_mfma_f32_16x16x32_bf16 v[14:17], v[118:121], v[190:193], v[14:17]
	v_mfma_f32_16x16x32_bf16 v[58:61], v[138:141], v[162:165], v[58:61]
	v_mfma_f32_16x16x32_bf16 v[58:61], v[142:145], v[166:169], v[58:61]
	v_mfma_f32_16x16x32_bf16 v[42:45], v[138:141], v[170:173], v[42:45]
	v_mfma_f32_16x16x32_bf16 v[42:45], v[142:145], v[174:177], v[42:45]
	v_mfma_f32_16x16x32_bf16 v[26:29], v[138:141], v[178:181], v[26:29]
	v_mfma_f32_16x16x32_bf16 v[26:29], v[142:145], v[182:185], v[26:29]
	v_mfma_f32_16x16x32_bf16 v[10:13], v[138:141], v[186:189], v[10:13]
	v_mfma_f32_16x16x32_bf16 v[10:13], v[142:145], v[190:193], v[10:13]
	v_mfma_f32_16x16x32_bf16 v[54:57], v[146:149], v[162:165], v[54:57]
	v_mfma_f32_16x16x32_bf16 v[54:57], v[150:153], v[166:169], v[54:57]
	v_mfma_f32_16x16x32_bf16 v[38:41], v[146:149], v[170:173], v[38:41]
	v_mfma_f32_16x16x32_bf16 v[38:41], v[150:153], v[174:177], v[38:41]
	v_mfma_f32_16x16x32_bf16 v[22:25], v[146:149], v[178:181], v[22:25]
	v_mfma_f32_16x16x32_bf16 v[22:25], v[150:153], v[182:185], v[22:25]
	v_mfma_f32_16x16x32_bf16 v[6:9], v[146:149], v[186:189], v[6:9]
	v_mfma_f32_16x16x32_bf16 v[6:9], v[150:153], v[190:193], v[6:9]
	v_mfma_f32_16x16x32_bf16 v[50:53], v[154:157], v[162:165], v[50:53]
	v_mfma_f32_16x16x32_bf16 v[50:53], v[158:161], v[166:169], v[50:53]
	v_mfma_f32_16x16x32_bf16 v[34:37], v[154:157], v[170:173], v[34:37]
	v_mfma_f32_16x16x32_bf16 v[34:37], v[158:161], v[174:177], v[34:37]
	v_mfma_f32_16x16x32_bf16 v[18:21], v[154:157], v[178:181], v[18:21]
	v_mfma_f32_16x16x32_bf16 v[18:21], v[158:161], v[182:185], v[18:21]
	v_mfma_f32_16x16x32_bf16 v[2:5], v[154:157], v[186:189], v[2:5]
	v_mfma_f32_16x16x32_bf16 v[2:5], v[158:161], v[190:193], v[2:5]
	s_setprio 0
	s_barrier
	s_add_i32 s18, 0, 0x18000
	s_add_i32 vcc_hi, 0, 0x1c000
	v_add_u32_e32 v142, s18, v245
	v_add_u32_e32 v158, vcc_hi, v245
	ds_read_b128 v[110:113], v142
	ds_read_b128 v[118:121], v142 offset:1024
	ds_read_b128 v[138:141], v142 offset:2048
	ds_read_b128 v[142:145], v142 offset:3072
	ds_read_b128 v[146:149], v158
	ds_read_b128 v[150:153], v158 offset:1024
	ds_read_b128 v[154:157], v158 offset:2048
	ds_read_b128 v[158:161], v158 offset:3072
	s_add_u32 s38, s46, s58
	s_addc_u32 s39, s47, 0
	s_mov_b32 m0, s94
	v_lshl_add_u64 v[222:223], s[38:39], 0, v[194:195]
	ds_read_b128 v[162:165], v247 offset:32768
	ds_read_b128 v[166:169], v247 offset:33792
	ds_read_b128 v[170:173], v247 offset:34816
	ds_read_b128 v[174:177], v247 offset:35840
	ds_read_b128 v[178:181], v247 offset:36864
	ds_read_b128 v[182:185], v247 offset:37888
	ds_read_b128 v[186:189], v247 offset:38912
	ds_read_b128 v[190:193], v247 offset:39936
	global_load_lds_dwordx4 v[222:223], off
	v_lshl_add_u64 v[222:223], s[38:39], 0, v[202:203]
	s_mov_b32 m0, s95
	s_nop 0
	global_load_lds_dwordx4 v[222:223], off
	s_waitcnt vmcnt(8)
	s_waitcnt lgkmcnt(0)
	s_setprio 1
	s_barrier
	v_mfma_f32_16x16x32_bf16 v[130:133], v[110:113], v[162:165], v[130:133]
	v_mfma_f32_16x16x32_bf16 v[130:133], v[118:121], v[166:169], v[130:133]
	v_mfma_f32_16x16x32_bf16 v[114:117], v[110:113], v[170:173], v[114:117]
	v_mfma_f32_16x16x32_bf16 v[114:117], v[118:121], v[174:177], v[114:117]
	v_mfma_f32_16x16x32_bf16 v[94:97], v[110:113], v[178:181], v[94:97]
	v_mfma_f32_16x16x32_bf16 v[94:97], v[118:121], v[182:185], v[94:97]
	v_mfma_f32_16x16x32_bf16 v[78:81], v[110:113], v[186:189], v[78:81]
	v_mfma_f32_16x16x32_bf16 v[78:81], v[118:121], v[190:193], v[78:81]
	v_mfma_f32_16x16x32_bf16 v[134:137], v[138:141], v[162:165], v[134:137]
	v_mfma_f32_16x16x32_bf16 v[134:137], v[142:145], v[166:169], v[134:137]
	v_mfma_f32_16x16x32_bf16 v[106:109], v[138:141], v[170:173], v[106:109]
	v_mfma_f32_16x16x32_bf16 v[106:109], v[142:145], v[174:177], v[106:109]
	v_mfma_f32_16x16x32_bf16 v[90:93], v[138:141], v[178:181], v[90:93]
	v_mfma_f32_16x16x32_bf16 v[90:93], v[142:145], v[182:185], v[90:93]
	v_mfma_f32_16x16x32_bf16 v[74:77], v[138:141], v[186:189], v[74:77]
	v_mfma_f32_16x16x32_bf16 v[74:77], v[142:145], v[190:193], v[74:77]
	v_mfma_f32_16x16x32_bf16 v[126:129], v[146:149], v[162:165], v[126:129]
	v_mfma_f32_16x16x32_bf16 v[126:129], v[150:153], v[166:169], v[126:129]
	v_mfma_f32_16x16x32_bf16 v[102:105], v[146:149], v[170:173], v[102:105]
	v_mfma_f32_16x16x32_bf16 v[102:105], v[150:153], v[174:177], v[102:105]
	v_mfma_f32_16x16x32_bf16 v[86:89], v[146:149], v[178:181], v[86:89]
	v_mfma_f32_16x16x32_bf16 v[86:89], v[150:153], v[182:185], v[86:89]
	v_mfma_f32_16x16x32_bf16 v[70:73], v[146:149], v[186:189], v[70:73]
	v_mfma_f32_16x16x32_bf16 v[70:73], v[150:153], v[190:193], v[70:73]
	v_mfma_f32_16x16x32_bf16 v[122:125], v[154:157], v[162:165], v[122:125]
	v_mfma_f32_16x16x32_bf16 v[122:125], v[158:161], v[166:169], v[122:125]
	v_mfma_f32_16x16x32_bf16 v[98:101], v[154:157], v[170:173], v[98:101]
	v_mfma_f32_16x16x32_bf16 v[98:101], v[158:161], v[174:177], v[98:101]
	v_mfma_f32_16x16x32_bf16 v[82:85], v[154:157], v[178:181], v[82:85]
	v_mfma_f32_16x16x32_bf16 v[82:85], v[158:161], v[182:185], v[82:85]
	v_mfma_f32_16x16x32_bf16 v[66:69], v[154:157], v[186:189], v[66:69]
	v_mfma_f32_16x16x32_bf16 v[66:69], v[158:161], v[190:193], v[66:69]
	s_setprio 0
	s_barrier
; #define PG8_STAGE(bufoff, gbase, voff) do { _Pragma("unroll") for (int _i = 0; _i < 2; ++_i) \
;         __builtin_amdgcn_global_load_lds((const unsigned*)((const char*)(gbase) + (voff)[_i]), (PG8_LAS unsigned*)(lds + (bufoff) + ldsw + _i * 8192), 16, 0, 0); } while (0)
; #define PG8_LDA(dst, b, h) do { _Pragma("unroll") for (int m = 0; m < 4; ++m) _Pragma("unroll") for (int k = 0; k < 2; ++k) dst[m][k] = *(const PG8_LAS bf16x8*)(lds + PG8_SA(b, h) + aoff + m * 2048 + k * 1024); } while (0)
; #define PG8_MMA(ai, bj, At, Bt) do { __builtin_amdgcn_s_setprio(1); _Pragma("unroll") for (int m = 0; m < 4; ++m) _Pragma("unroll") for (int n = 0; n < 2; ++n) _Pragma("unroll") for (int k = 0; k < 2; ++k) \
;         acc[ai][bj][m][n] = __builtin_amdgcn_mfma_f32_16x16x32_bf16(Bt[n][k], At[m][k], acc[ai][bj][m][n], 0, 0, 0); __builtin_amdgcn_s_setprio(0); } while (0)
; #define PG8_WAIT_V(n) asm volatile("s_waitcnt vmcnt(" #n ")" ::: "memory")
; #define PG8_WAIT_L(n) asm volatile("s_waitcnt lgkmcnt(" #n ")" ::: "memory")
; #define PG8_BAR __builtin_amdgcn_s_barrier()
; #define PG8_SCHED __builtin_amdgcn_sched_barrier(0)
; template <class Epi, class Sched, bool ALIGN_EPI = false, bool SP2 = false>
; __device__ __forceinline__ void gemm_phase(PG8_LAS unsigned char* lds, const Gemm g, const Sched& S, const Epi& E) {
;     ...
;             PG8_LDA(At, 1, 1); PG8_STAGE(PG8_SB(1, 0), b3, voffB); PG8_STAGE(PG8_SB(1, 1), b3 + hstep, voffB); PG8_STAGE(PG8_SA(1, 0), a3, voffA);
;             PG8_WAIT_V(8); PG8_WAIT_L(0); PG8_BAR; PG8_MMA(1, 0, At, B0); PG8_MMA(1, 1, At, B1); PG8_BAR; PG8_SCHED;
;     ...
;         if constexpr (ALIGN_EPI) { if (wr == 0) PG8_BAR; }
	s_add_i32 s18, s18, s6
	v_lshl_add_u64 v[210:211], v[210:211], 0, s[30:31]
	s_mov_b32 m0, s18
	ds_read_b128 v[162:165], v247 offset:49152
	ds_read_b128 v[166:169], v247 offset:50176
	ds_read_b128 v[170:173], v247 offset:51200
	ds_read_b128 v[174:177], v247 offset:52224
	ds_read_b128 v[178:181], v247 offset:53248
	ds_read_b128 v[182:185], v247 offset:54272
	ds_read_b128 v[186:189], v247 offset:55296
	ds_read_b128 v[190:193], v247 offset:56320
	global_load_lds_dwordx4 v[210:211], off
	v_lshl_add_u64 v[210:211], v[212:213], 0, s[30:31]
	s_add_i32 m0, s18, 0x2000
	s_add_i32 s18, vcc_hi, s6
	global_load_lds_dwordx4 v[210:211], off
	v_lshl_add_u64 v[210:211], v[214:215], 0, s[30:31]
	s_mov_b32 m0, s18
	s_nop 0
	global_load_lds_dwordx4 v[210:211], off
	v_lshl_add_u64 v[210:211], v[216:217], 0, s[30:31]
	s_add_i32 m0, s18, 0x2000
	s_nop 0
	global_load_lds_dwordx4 v[210:211], off
	v_lshl_add_u64 v[210:211], v[218:219], 0, s[30:31]
	s_mov_b32 m0, s97
	s_nop 0
	global_load_lds_dwordx4 v[210:211], off
	v_lshl_add_u64 v[210:211], v[220:221], 0, s[30:31]
	s_mov_b32 m0, s98
	s_nop 0
	global_load_lds_dwordx4 v[210:211], off
	s_waitcnt vmcnt(8)
	s_waitcnt lgkmcnt(0)
	s_setprio 1
	s_barrier
	v_mfma_f32_16x16x32_bf16 v[62:65], v[110:113], v[162:165], v[62:65]
	v_mfma_f32_16x16x32_bf16 v[62:65], v[118:121], v[166:169], v[62:65]
	v_mfma_f32_16x16x32_bf16 v[46:49], v[110:113], v[170:173], v[46:49]
	v_mfma_f32_16x16x32_bf16 v[46:49], v[118:121], v[174:177], v[46:49]
	v_mfma_f32_16x16x32_bf16 v[30:33], v[110:113], v[178:181], v[30:33]
	v_mfma_f32_16x16x32_bf16 v[30:33], v[118:121], v[182:185], v[30:33]
	v_mfma_f32_16x16x32_bf16 v[14:17], v[110:113], v[186:189], v[14:17]
	v_mfma_f32_16x16x32_bf16 v[14:17], v[118:121], v[190:193], v[14:17]
	v_mfma_f32_16x16x32_bf16 v[58:61], v[138:141], v[162:165], v[58:61]
	v_mfma_f32_16x16x32_bf16 v[58:61], v[142:145], v[166:169], v[58:61]
	v_mfma_f32_16x16x32_bf16 v[42:45], v[138:141], v[170:173], v[42:45]
	v_mfma_f32_16x16x32_bf16 v[42:45], v[142:145], v[174:177], v[42:45]
	v_mfma_f32_16x16x32_bf16 v[26:29], v[138:141], v[178:181], v[26:29]
	v_mfma_f32_16x16x32_bf16 v[26:29], v[142:145], v[182:185], v[26:29]
	v_mfma_f32_16x16x32_bf16 v[10:13], v[138:141], v[186:189], v[10:13]
	v_mfma_f32_16x16x32_bf16 v[10:13], v[142:145], v[190:193], v[10:13]
	v_mfma_f32_16x16x32_bf16 v[54:57], v[146:149], v[162:165], v[54:57]
	v_mfma_f32_16x16x32_bf16 v[54:57], v[150:153], v[166:169], v[54:57]
	v_mfma_f32_16x16x32_bf16 v[38:41], v[146:149], v[170:173], v[38:41]
	v_mfma_f32_16x16x32_bf16 v[38:41], v[150:153], v[174:177], v[38:41]
	v_mfma_f32_16x16x32_bf16 v[22:25], v[146:149], v[178:181], v[22:25]
	v_mfma_f32_16x16x32_bf16 v[22:25], v[150:153], v[182:185], v[22:25]
	v_mfma_f32_16x16x32_bf16 v[6:9], v[146:149], v[186:189], v[6:9]
	v_mfma_f32_16x16x32_bf16 v[6:9], v[150:153], v[190:193], v[6:9]
	v_mfma_f32_16x16x32_bf16 v[50:53], v[154:157], v[162:165], v[50:53]
	v_mfma_f32_16x16x32_bf16 v[50:53], v[158:161], v[166:169], v[50:53]
	v_mfma_f32_16x16x32_bf16 v[34:37], v[154:157], v[170:173], v[34:37]
	v_mfma_f32_16x16x32_bf16 v[34:37], v[158:161], v[174:177], v[34:37]
	v_mfma_f32_16x16x32_bf16 v[18:21], v[154:157], v[178:181], v[18:21]
	v_mfma_f32_16x16x32_bf16 v[18:21], v[158:161], v[182:185], v[18:21]
	v_mfma_f32_16x16x32_bf16 v[2:5], v[154:157], v[186:189], v[2:5]
	v_mfma_f32_16x16x32_bf16 v[2:5], v[158:161], v[190:193], v[2:5]
	s_setprio 0
	s_barrier
	s_add_u32 s48, s48, 0x100
	s_addc_u32 s49, s49, 0
	s_add_u32 s50, s50, 0x100
	s_addc_u32 s51, s51, 0
	s_cmp_ge_u32 vcc_lo, s96
	s_mov_b32 s46, vcc_lo
	s_cbranch_scc0 .LBB0_274
	s_and_b64 vcc, exec, s[72:73]
	s_cbranch_vccz .LBB0_277
	s_barrier

; #define PG8_STAGE(bufoff, gbase, voff) do { _Pragma("unroll") for (int _i = 0; _i < 2; ++_i) \
;         __builtin_amdgcn_global_load_lds((const unsigned*)((const char*)(gbase) + (voff)[_i]), (PG8_LAS unsigned*)(lds + (bufoff) + ldsw + _i * 8192), 16, 0, 0); } while (0)
; #define PG8_LDA(dst, b, h) do { _Pragma("unroll") for (int m = 0; m < 4; ++m) _Pragma("unroll") for (int k = 0; k < 2; ++k) dst[m][k] = *(const PG8_LAS bf16x8*)(lds + PG8_SA(b, h) + aoff + m * 2048 + k * 1024); } while (0)
; #define PG8_LDB(dst, b, h) do { _Pragma("unroll") for (int n = 0; n < 2; ++n) _Pragma("unroll") for (int k = 0; k < 2; ++k) dst[n][k] = *(const PG8_LAS bf16x8*)(lds + PG8_SB(b, h) + boff + n * 2048 + k * 1024); } while (0)
; #define PG8_MMA(ai, bj, At, Bt) do { __builtin_amdgcn_s_setprio(1); _Pragma("unroll") for (int m = 0; m < 4; ++m) _Pragma("unroll") for (int n = 0; n < 2; ++n) _Pragma("unroll") for (int k = 0; k < 2; ++k) \
;         acc[ai][bj][m][n] = __builtin_amdgcn_mfma_f32_16x16x32_bf16(Bt[n][k], At[m][k], acc[ai][bj][m][n], 0, 0, 0); __builtin_amdgcn_s_setprio(0); } while (0)
; #define PG8_WAIT_V(n) asm volatile("s_waitcnt vmcnt(" #n ")" ::: "memory")
; #define PG8_WAIT_L(n) asm volatile("s_waitcnt lgkmcnt(" #n ")" ::: "memory")
; #define PG8_BAR __builtin_amdgcn_s_barrier()
; template <class Epi, class Sched, bool ALIGN_EPI = false, bool SP2 = false>
; __device__ __forceinline__ void gemm_phase(PG8_LAS unsigned char* lds, const Gemm g, const Sched& S, const Epi& E) {
;     ...
;             const char* a1 = cA + (size_t)(t + 1) * kstep;
;             const char* a2 = last ? nA : cA + (size_t)(t + 2) * kstep; const char* b2 = last ? nB : cB + (size_t)(t + 2) * kstep;
;             const char* a3 = a2 + kstep; const char* b3 = b2 + kstep;
;             if (last && has_next) S.a_ready(nxt);
;             if constexpr (SP2) {
;             PG8_LDB(B0, 0, 0); PG8_LDB(B1, 0, 1); PG8_SCHED; PG8_LDA(At, 0, 0); PG8_STAGE(PG8_SA(1, 1), a1 + hstep, voffA);
;             PG8_WAIT_V(8); PG8_WAIT_L(0); PG8_BAR; PG8_MMA(0, 0, At, B0); PG8_MMA(0, 1, At, B1); PG8_BAR; PG8_SCHED;
;             PG8_LDA(At, 0, 1); PG8_STAGE(PG8_SB(0, 0), b2, voffB); PG8_STAGE(PG8_SB(0, 1), b2 + hstep, voffB); PG8_STAGE(PG8_SA(0, 0), a2, voffA);
;             PG8_WAIT_V(8); PG8_WAIT_L(0); PG8_BAR; PG8_MMA(1, 0, At, B0); PG8_MMA(1, 1, At, B1); PG8_BAR; PG8_SCHED;
.LBB0_408:
	s_add_u32 s38, s48, 0xfffc0080
	s_addc_u32 s39, s49, -1
	s_add_i32 s85, 0, 0x10000
	s_cmp_eq_u32 s84, 12
	s_cselect_b32 s73, s21, s39
	s_cselect_b32 s72, s27, s38
	v_add_u32_e32 v0, s85, v167
	s_cselect_b32 s47, s29, s69
	s_cselect_b32 s46, s33, s53
	s_add_i32 s38, 0, 0x14000
	ds_read_b128 v[142:145], v0
	ds_read_b128 v[146:149], v0 offset:1024
	ds_read_b128 v[150:153], v0 offset:2048
	ds_read_b128 v[154:157], v0 offset:3072
	v_add_u32_e32 v0, s38, v167
	ds_read_b128 v[158:161], v0
	ds_read_b128 v[162:165], v0 offset:1024
	ds_read_b128 v[172:175], v0 offset:2048
	ds_read_b128 v[176:179], v0 offset:3072
	v_lshl_add_u64 v[218:219], s[48:49], 0, v[138:139]
	s_add_i32 m0, s76, 0xc000
	ds_read_b128 v[180:183], v170
	ds_read_b128 v[184:187], v170 offset:1024
	ds_read_b128 v[188:191], v170 offset:2048
	ds_read_b128 v[192:195], v170 offset:3072
	ds_read_b128 v[202:205], v170 offset:4096
	ds_read_b128 v[206:209], v170 offset:5120
	ds_read_b128 v[210:213], v170 offset:6144
	ds_read_b128 v[214:217], v170 offset:7168
	global_load_lds_dwordx4 v[218:219], off
	v_lshl_add_u64 v[218:219], s[48:49], 0, v[140:141]
	s_add_i32 m0, s76, 0xe000
	s_nop 0
	global_load_lds_dwordx4 v[218:219], off
	s_waitcnt vmcnt(8)
	s_waitcnt lgkmcnt(0)
	s_setprio 1
	s_barrier
	v_mfma_f32_16x16x32_bf16 v[122:125], v[142:145], v[180:183], v[122:125]
	v_mfma_f32_16x16x32_bf16 v[122:125], v[146:149], v[184:187], v[122:125]
	v_mfma_f32_16x16x32_bf16 v[106:109], v[142:145], v[188:191], v[106:109]
	v_mfma_f32_16x16x32_bf16 v[106:109], v[146:149], v[192:195], v[106:109]
	v_mfma_f32_16x16x32_bf16 v[90:93], v[142:145], v[202:205], v[90:93]
	v_mfma_f32_16x16x32_bf16 v[90:93], v[146:149], v[206:209], v[90:93]
	v_mfma_f32_16x16x32_bf16 v[74:77], v[142:145], v[210:213], v[74:77]
	v_mfma_f32_16x16x32_bf16 v[74:77], v[146:149], v[214:217], v[74:77]
	v_mfma_f32_16x16x32_bf16 v[126:129], v[150:153], v[180:183], v[126:129]
	v_mfma_f32_16x16x32_bf16 v[126:129], v[154:157], v[184:187], v[126:129]
	v_mfma_f32_16x16x32_bf16 v[110:113], v[150:153], v[188:191], v[110:113]
	v_mfma_f32_16x16x32_bf16 v[110:113], v[154:157], v[192:195], v[110:113]
	v_mfma_f32_16x16x32_bf16 v[94:97], v[150:153], v[202:205], v[94:97]
	v_mfma_f32_16x16x32_bf16 v[94:97], v[154:157], v[206:209], v[94:97]
	v_mfma_f32_16x16x32_bf16 v[78:81], v[150:153], v[210:213], v[78:81]
	v_mfma_f32_16x16x32_bf16 v[78:81], v[154:157], v[214:217], v[78:81]
	v_mfma_f32_16x16x32_bf16 v[114:117], v[158:161], v[180:183], v[114:117]
	v_mfma_f32_16x16x32_bf16 v[114:117], v[162:165], v[184:187], v[114:117]
	v_mfma_f32_16x16x32_bf16 v[98:101], v[158:161], v[188:191], v[98:101]
	v_mfma_f32_16x16x32_bf16 v[98:101], v[162:165], v[192:195], v[98:101]
	v_mfma_f32_16x16x32_bf16 v[82:85], v[158:161], v[202:205], v[82:85]
	v_mfma_f32_16x16x32_bf16 v[82:85], v[162:165], v[206:209], v[82:85]
	v_mfma_f32_16x16x32_bf16 v[66:69], v[158:161], v[210:213], v[66:69]
	v_mfma_f32_16x16x32_bf16 v[66:69], v[162:165], v[214:217], v[66:69]
	v_mfma_f32_16x16x32_bf16 v[118:121], v[172:175], v[180:183], v[118:121]
	v_mfma_f32_16x16x32_bf16 v[118:121], v[176:179], v[184:187], v[118:121]
	v_mfma_f32_16x16x32_bf16 v[102:105], v[172:175], v[188:191], v[102:105]
	v_mfma_f32_16x16x32_bf16 v[102:105], v[176:179], v[192:195], v[102:105]
	v_mfma_f32_16x16x32_bf16 v[86:89], v[172:175], v[202:205], v[86:89]
	v_mfma_f32_16x16x32_bf16 v[86:89], v[176:179], v[206:209], v[86:89]
	v_mfma_f32_16x16x32_bf16 v[70:73], v[172:175], v[210:213], v[70:73]
	v_mfma_f32_16x16x32_bf16 v[70:73], v[176:179], v[214:217], v[70:73]
	s_setprio 0
	s_barrier
	s_add_i32 s39, s85, s75
	v_lshl_add_u64 v[218:219], s[46:47], 0, v[134:135]
	s_mov_b32 m0, s39
	ds_read_b128 v[180:183], v170 offset:16384
	ds_read_b128 v[184:187], v170 offset:17408
	ds_read_b128 v[188:191], v170 offset:18432
	ds_read_b128 v[192:195], v170 offset:19456
	ds_read_b128 v[202:205], v170 offset:20480
	ds_read_b128 v[206:209], v170 offset:21504
	ds_read_b128 v[210:213], v170 offset:22528
	ds_read_b128 v[214:217], v170 offset:23552
	global_load_lds_dwordx4 v[218:219], off
	s_add_i32 m0, s39, 0x2000
	s_add_u32 s92, s46, 0x40000
	v_lshl_add_u64 v[220:221], s[46:47], 0, v[130:131]
	s_addc_u32 s93, s47, 0
	s_add_i32 s38, s38, s75
	global_load_lds_dwordx4 v[220:221], off
	v_lshl_add_u64 v[222:223], s[92:93], 0, v[134:135]
	s_mov_b32 m0, s38
	v_lshl_add_u64 v[224:225], s[72:73], 0, v[132:133]
	global_load_lds_dwordx4 v[222:223], off
	v_lshl_add_u64 v[222:223], s[92:93], 0, v[130:131]
	s_add_i32 m0, s38, 0x2000
	s_nop 0
	global_load_lds_dwordx4 v[222:223], off
	v_lshl_add_u64 v[222:223], s[72:73], 0, v[136:137]
	s_mov_b32 m0, s76
	s_nop 0
	global_load_lds_dwordx4 v[222:223], off
	s_mov_b32 m0, s77
	s_nop 0
	global_load_lds_dwordx4 v[224:225], off
	s_waitcnt vmcnt(8)
	s_waitcnt lgkmcnt(0)
	s_setprio 1
	s_barrier
; #define PG8_STAGE(bufoff, gbase, voff) do { _Pragma("unroll") for (int _i = 0; _i < 2; ++_i) \
;         __builtin_amdgcn_global_load_lds((const unsigned*)((const char*)(gbase) + (voff)[_i]), (PG8_LAS unsigned*)(lds + (bufoff) + ldsw + _i * 8192), 16, 0, 0); } while (0)
; #define PG8_LDA(dst, b, h) do { _Pragma("unroll") for (int m = 0; m < 4; ++m) _Pragma("unroll") for (int k = 0; k < 2; ++k) dst[m][k] = *(const PG8_LAS bf16x8*)(lds + PG8_SA(b, h) + aoff + m * 2048 + k * 1024); } while (0)
; #define PG8_LDB(dst, b, h) do { _Pragma("unroll") for (int n = 0; n < 2; ++n) _Pragma("unroll") for (int k = 0; k < 2; ++k) dst[n][k] = *(const PG8_LAS bf16x8*)(lds + PG8_SB(b, h) + boff + n * 2048 + k * 1024); } while (0)
; #define PG8_MMA(ai, bj, At, Bt) do { __builtin_amdgcn_s_setprio(1); _Pragma("unroll") for (int m = 0; m < 4; ++m) _Pragma("unroll") for (int n = 0; n < 2; ++n) _Pragma("unroll") for (int k = 0; k < 2; ++k) \
;         acc[ai][bj][m][n] = __builtin_amdgcn_mfma_f32_16x16x32_bf16(Bt[n][k], At[m][k], acc[ai][bj][m][n], 0, 0, 0); __builtin_amdgcn_s_setprio(0); } while (0)
; #define PG8_WAIT_V(n) asm volatile("s_waitcnt vmcnt(" #n ")" ::: "memory")
; #define PG8_WAIT_L(n) asm volatile("s_waitcnt lgkmcnt(" #n ")" ::: "memory")
; #define PG8_BAR __builtin_amdgcn_s_barrier()
; #define PG8_SCHED __builtin_amdgcn_sched_barrier(0)
; template <class Epi, class Sched, bool ALIGN_EPI = false, bool SP2 = false>
; __device__ __forceinline__ void gemm_phase(PG8_LAS unsigned char* lds, const Gemm g, const Sched& S, const Epi& E) {
;     ...
;             PG8_WAIT_V(8); PG8_WAIT_L(0); PG8_BAR; PG8_MMA(1, 0, At, B0); PG8_MMA(1, 1, At, B1); PG8_BAR; PG8_SCHED;
;             PG8_LDB(B0, 1, 0); PG8_LDB(B1, 1, 1); PG8_SCHED; PG8_LDA(At, 1, 0); PG8_STAGE(PG8_SA(0, 1), a2 + hstep, voffA);
;             PG8_WAIT_V(8); PG8_WAIT_L(0); PG8_BAR; PG8_MMA(0, 0, At, B0); PG8_MMA(0, 1, At, B1); PG8_BAR; PG8_SCHED;
	v_mfma_f32_16x16x32_bf16 v[58:61], v[142:145], v[180:183], v[58:61]
	v_mfma_f32_16x16x32_bf16 v[58:61], v[146:149], v[184:187], v[58:61]
	v_mfma_f32_16x16x32_bf16 v[42:45], v[142:145], v[188:191], v[42:45]
	v_mfma_f32_16x16x32_bf16 v[42:45], v[146:149], v[192:195], v[42:45]
	v_mfma_f32_16x16x32_bf16 v[26:29], v[142:145], v[202:205], v[26:29]
	v_mfma_f32_16x16x32_bf16 v[26:29], v[146:149], v[206:209], v[26:29]
	v_mfma_f32_16x16x32_bf16 v[10:13], v[142:145], v[210:213], v[10:13]
	v_mfma_f32_16x16x32_bf16 v[10:13], v[146:149], v[214:217], v[10:13]
	v_mfma_f32_16x16x32_bf16 v[62:65], v[150:153], v[180:183], v[62:65]
	v_mfma_f32_16x16x32_bf16 v[62:65], v[154:157], v[184:187], v[62:65]
	v_mfma_f32_16x16x32_bf16 v[46:49], v[150:153], v[188:191], v[46:49]
	v_mfma_f32_16x16x32_bf16 v[46:49], v[154:157], v[192:195], v[46:49]
	v_mfma_f32_16x16x32_bf16 v[30:33], v[150:153], v[202:205], v[30:33]
	v_mfma_f32_16x16x32_bf16 v[30:33], v[154:157], v[206:209], v[30:33]
	v_mfma_f32_16x16x32_bf16 v[14:17], v[150:153], v[210:213], v[14:17]
	v_mfma_f32_16x16x32_bf16 v[14:17], v[154:157], v[214:217], v[14:17]
	v_mfma_f32_16x16x32_bf16 v[50:53], v[158:161], v[180:183], v[50:53]
	v_mfma_f32_16x16x32_bf16 v[50:53], v[162:165], v[184:187], v[50:53]
	v_mfma_f32_16x16x32_bf16 v[34:37], v[158:161], v[188:191], v[34:37]
	v_mfma_f32_16x16x32_bf16 v[34:37], v[162:165], v[192:195], v[34:37]
	v_mfma_f32_16x16x32_bf16 v[18:21], v[158:161], v[202:205], v[18:21]
	v_mfma_f32_16x16x32_bf16 v[18:21], v[162:165], v[206:209], v[18:21]
	v_mfma_f32_16x16x32_bf16 v[2:5], v[158:161], v[210:213], v[2:5]
	v_mfma_f32_16x16x32_bf16 v[2:5], v[162:165], v[214:217], v[2:5]
	v_mfma_f32_16x16x32_bf16 v[54:57], v[172:175], v[180:183], v[54:57]
	v_mfma_f32_16x16x32_bf16 v[54:57], v[176:179], v[184:187], v[54:57]
	v_mfma_f32_16x16x32_bf16 v[38:41], v[172:175], v[188:191], v[38:41]
	v_mfma_f32_16x16x32_bf16 v[38:41], v[176:179], v[192:195], v[38:41]
	v_mfma_f32_16x16x32_bf16 v[22:25], v[172:175], v[202:205], v[22:25]
	v_mfma_f32_16x16x32_bf16 v[22:25], v[176:179], v[206:209], v[22:25]
	v_mfma_f32_16x16x32_bf16 v[6:9], v[172:175], v[210:213], v[6:9]
	v_mfma_f32_16x16x32_bf16 v[6:9], v[176:179], v[214:217], v[6:9]
	s_setprio 0
	s_barrier
	s_add_i32 s38, 0, 0x18000
	v_add_u32_e32 v0, s38, v167
	s_add_i32 s39, 0, 0x1c000
	ds_read_b128 v[142:145], v0
	ds_read_b128 v[146:149], v0 offset:1024
	ds_read_b128 v[150:153], v0 offset:2048
	ds_read_b128 v[154:157], v0 offset:3072
	v_add_u32_e32 v0, s39, v167
	ds_read_b128 v[158:161], v0
	ds_read_b128 v[162:165], v0 offset:1024
	ds_read_b128 v[172:175], v0 offset:2048
	ds_read_b128 v[176:179], v0 offset:3072
	s_add_u32 s72, s72, 0x40000
	s_addc_u32 s73, s73, 0
	s_mov_b32 m0, s78
	v_lshl_add_u64 v[226:227], s[72:73], 0, v[136:137]
	ds_read_b128 v[180:183], v170 offset:32768
	ds_read_b128 v[184:187], v170 offset:33792
	ds_read_b128 v[188:191], v170 offset:34816
	ds_read_b128 v[192:195], v170 offset:35840
	ds_read_b128 v[202:205], v170 offset:36864
	ds_read_b128 v[206:209], v170 offset:37888
	ds_read_b128 v[210:213], v170 offset:38912
	ds_read_b128 v[214:217], v170 offset:39936
	global_load_lds_dwordx4 v[226:227], off
	v_lshl_add_u64 v[226:227], s[72:73], 0, v[132:133]
	s_mov_b32 m0, s79
	s_nop 0
	global_load_lds_dwordx4 v[226:227], off
	s_waitcnt vmcnt(8)
	s_waitcnt lgkmcnt(0)
	s_setprio 1
	s_barrier
	v_mfma_f32_16x16x32_bf16 v[122:125], v[142:145], v[180:183], v[122:125]
	v_mfma_f32_16x16x32_bf16 v[122:125], v[146:149], v[184:187], v[122:125]
	v_mfma_f32_16x16x32_bf16 v[106:109], v[142:145], v[188:191], v[106:109]
	v_mfma_f32_16x16x32_bf16 v[106:109], v[146:149], v[192:195], v[106:109]
	v_mfma_f32_16x16x32_bf16 v[90:93], v[142:145], v[202:205], v[90:93]
	v_mfma_f32_16x16x32_bf16 v[90:93], v[146:149], v[206:209], v[90:93]
	v_mfma_f32_16x16x32_bf16 v[74:77], v[142:145], v[210:213], v[74:77]
	v_mfma_f32_16x16x32_bf16 v[74:77], v[146:149], v[214:217], v[74:77]
	v_mfma_f32_16x16x32_bf16 v[126:129], v[150:153], v[180:183], v[126:129]
	v_mfma_f32_16x16x32_bf16 v[126:129], v[154:157], v[184:187], v[126:129]
	v_mfma_f32_16x16x32_bf16 v[110:113], v[150:153], v[188:191], v[110:113]
	v_mfma_f32_16x16x32_bf16 v[110:113], v[154:157], v[192:195], v[110:113]
	v_mfma_f32_16x16x32_bf16 v[94:97], v[150:153], v[202:205], v[94:97]
	v_mfma_f32_16x16x32_bf16 v[94:97], v[154:157], v[206:209], v[94:97]
	v_mfma_f32_16x16x32_bf16 v[78:81], v[150:153], v[210:213], v[78:81]
	v_mfma_f32_16x16x32_bf16 v[78:81], v[154:157], v[214:217], v[78:81]
	v_mfma_f32_16x16x32_bf16 v[114:117], v[158:161], v[180:183], v[114:117]
	v_mfma_f32_16x16x32_bf16 v[114:117], v[162:165], v[184:187], v[114:117]
	v_mfma_f32_16x16x32_bf16 v[98:101], v[158:161], v[188:191], v[98:101]
	v_mfma_f32_16x16x32_bf16 v[98:101], v[162:165], v[192:195], v[98:101]
	v_mfma_f32_16x16x32_bf16 v[82:85], v[158:161], v[202:205], v[82:85]
	v_mfma_f32_16x16x32_bf16 v[82:85], v[162:165], v[206:209], v[82:85]
	v_mfma_f32_16x16x32_bf16 v[66:69], v[158:161], v[210:213], v[66:69]
	v_mfma_f32_16x16x32_bf16 v[66:69], v[162:165], v[214:217], v[66:69]
	v_mfma_f32_16x16x32_bf16 v[118:121], v[172:175], v[180:183], v[118:121]
	v_mfma_f32_16x16x32_bf16 v[118:121], v[176:179], v[184:187], v[118:121]
	v_mfma_f32_16x16x32_bf16 v[102:105], v[172:175], v[188:191], v[102:105]
	v_mfma_f32_16x16x32_bf16 v[102:105], v[176:179], v[192:195], v[102:105]
	v_mfma_f32_16x16x32_bf16 v[86:89], v[172:175], v[202:205], v[86:89]
	v_mfma_f32_16x16x32_bf16 v[86:89], v[176:179], v[206:209], v[86:89]
	v_mfma_f32_16x16x32_bf16 v[70:73], v[172:175], v[210:213], v[70:73]
	v_mfma_f32_16x16x32_bf16 v[70:73], v[176:179], v[214:217], v[70:73]
	s_setprio 0
	s_barrier
; #define PG8_STAGE(bufoff, gbase, voff) do { _Pragma("unroll") for (int _i = 0; _i < 2; ++_i) \
;         __builtin_amdgcn_global_load_lds((const unsigned*)((const char*)(gbase) + (voff)[_i]), (PG8_LAS unsigned*)(lds + (bufoff) + ldsw + _i * 8192), 16, 0, 0); } while (0)
; #define PG8_LDA(dst, b, h) do { _Pragma("unroll") for (int m = 0; m < 4; ++m) _Pragma("unroll") for (int k = 0; k < 2; ++k) dst[m][k] = *(const PG8_LAS bf16x8*)(lds + PG8_SA(b, h) + aoff + m * 2048 + k * 1024); } while (0)
; #define PG8_MMA(ai, bj, At, Bt) do { __builtin_amdgcn_s_setprio(1); _Pragma("unroll") for (int m = 0; m < 4; ++m) _Pragma("unroll") for (int n = 0; n < 2; ++n) _Pragma("unroll") for (int k = 0; k < 2; ++k) \
;         acc[ai][bj][m][n] = __builtin_amdgcn_mfma_f32_16x16x32_bf16(Bt[n][k], At[m][k], acc[ai][bj][m][n], 0, 0, 0); __builtin_amdgcn_s_setprio(0); } while (0)
; #define PG8_WAIT_V(n) asm volatile("s_waitcnt vmcnt(" #n ")" ::: "memory")
; #define PG8_WAIT_L(n) asm volatile("s_waitcnt lgkmcnt(" #n ")" ::: "memory")
; #define PG8_BAR __builtin_amdgcn_s_barrier()
; #define PG8_SCHED __builtin_amdgcn_sched_barrier(0)
; template <class Epi, class Sched, bool ALIGN_EPI = false, bool SP2 = false>
; __device__ __forceinline__ void gemm_phase(PG8_LAS unsigned char* lds, const Gemm g, const Sched& S, const Epi& E) {
;     ...
;             PG8_LDA(At, 1, 1); PG8_STAGE(PG8_SB(1, 0), b3, voffB); PG8_STAGE(PG8_SB(1, 1), b3 + hstep, voffB); PG8_STAGE(PG8_SA(1, 0), a3, voffA);
;             PG8_WAIT_V(8); PG8_WAIT_L(0); PG8_BAR; PG8_MMA(1, 0, At, B0); PG8_MMA(1, 1, At, B1); PG8_BAR; PG8_SCHED;
;     ...
;         if constexpr (ALIGN_EPI) { if (wr == 0) PG8_BAR; }
	s_add_i32 s38, s38, s75
	v_lshl_add_u64 v[218:219], v[218:219], 0, s[30:31]
	s_mov_b32 m0, s38
	ds_read_b128 v[180:183], v170 offset:49152
	ds_read_b128 v[184:187], v170 offset:50176
	ds_read_b128 v[188:191], v170 offset:51200
	ds_read_b128 v[192:195], v170 offset:52224
	ds_read_b128 v[202:205], v170 offset:53248
	ds_read_b128 v[206:209], v170 offset:54272
	ds_read_b128 v[210:213], v170 offset:55296
	ds_read_b128 v[214:217], v170 offset:56320
	global_load_lds_dwordx4 v[218:219], off
	s_add_i32 m0, s38, 0x2000
	s_add_u32 s46, s46, 0x40080
	v_lshl_add_u64 v[218:219], v[220:221], 0, s[30:31]
	s_addc_u32 s47, s47, 0
	s_add_i32 s38, s39, s75
	global_load_lds_dwordx4 v[218:219], off
	v_lshl_add_u64 v[218:219], s[46:47], 0, v[134:135]
	s_mov_b32 m0, s38
	s_nop 0
	global_load_lds_dwordx4 v[218:219], off
	v_lshl_add_u64 v[218:219], s[46:47], 0, v[130:131]
	s_add_i32 m0, s38, 0x2000
	s_nop 0
	global_load_lds_dwordx4 v[218:219], off
	v_lshl_add_u64 v[218:219], v[222:223], 0, s[30:31]
	s_mov_b32 m0, s80
	s_nop 0
	global_load_lds_dwordx4 v[218:219], off
	v_lshl_add_u64 v[218:219], v[224:225], 0, s[30:31]
	s_mov_b32 m0, s81
	s_nop 0
	global_load_lds_dwordx4 v[218:219], off
	s_waitcnt vmcnt(8)
	s_waitcnt lgkmcnt(0)
	s_setprio 1
	s_barrier
	v_mfma_f32_16x16x32_bf16 v[58:61], v[142:145], v[180:183], v[58:61]
	v_mfma_f32_16x16x32_bf16 v[58:61], v[146:149], v[184:187], v[58:61]
	v_mfma_f32_16x16x32_bf16 v[42:45], v[142:145], v[188:191], v[42:45]
	v_mfma_f32_16x16x32_bf16 v[42:45], v[146:149], v[192:195], v[42:45]
	v_mfma_f32_16x16x32_bf16 v[26:29], v[142:145], v[202:205], v[26:29]
	v_mfma_f32_16x16x32_bf16 v[26:29], v[146:149], v[206:209], v[26:29]
	v_mfma_f32_16x16x32_bf16 v[10:13], v[142:145], v[210:213], v[10:13]
	v_mfma_f32_16x16x32_bf16 v[10:13], v[146:149], v[214:217], v[10:13]
	v_mfma_f32_16x16x32_bf16 v[62:65], v[150:153], v[180:183], v[62:65]
	v_mfma_f32_16x16x32_bf16 v[62:65], v[154:157], v[184:187], v[62:65]
	v_mfma_f32_16x16x32_bf16 v[46:49], v[150:153], v[188:191], v[46:49]
	v_mfma_f32_16x16x32_bf16 v[46:49], v[154:157], v[192:195], v[46:49]
	v_mfma_f32_16x16x32_bf16 v[30:33], v[150:153], v[202:205], v[30:33]
	v_mfma_f32_16x16x32_bf16 v[30:33], v[154:157], v[206:209], v[30:33]
	v_mfma_f32_16x16x32_bf16 v[14:17], v[150:153], v[210:213], v[14:17]
	v_mfma_f32_16x16x32_bf16 v[14:17], v[154:157], v[214:217], v[14:17]
	v_mfma_f32_16x16x32_bf16 v[50:53], v[158:161], v[180:183], v[50:53]
	v_mfma_f32_16x16x32_bf16 v[50:53], v[162:165], v[184:187], v[50:53]
	v_mfma_f32_16x16x32_bf16 v[34:37], v[158:161], v[188:191], v[34:37]
	v_mfma_f32_16x16x32_bf16 v[34:37], v[162:165], v[192:195], v[34:37]
	v_mfma_f32_16x16x32_bf16 v[18:21], v[158:161], v[202:205], v[18:21]
	v_mfma_f32_16x16x32_bf16 v[18:21], v[162:165], v[206:209], v[18:21]
	v_mfma_f32_16x16x32_bf16 v[2:5], v[158:161], v[210:213], v[2:5]
	v_mfma_f32_16x16x32_bf16 v[2:5], v[162:165], v[214:217], v[2:5]
	v_mfma_f32_16x16x32_bf16 v[54:57], v[172:175], v[180:183], v[54:57]
	v_mfma_f32_16x16x32_bf16 v[54:57], v[176:179], v[184:187], v[54:57]
	v_mfma_f32_16x16x32_bf16 v[38:41], v[172:175], v[188:191], v[38:41]
	v_mfma_f32_16x16x32_bf16 v[38:41], v[176:179], v[192:195], v[38:41]
	v_mfma_f32_16x16x32_bf16 v[22:25], v[172:175], v[202:205], v[22:25]
	v_mfma_f32_16x16x32_bf16 v[22:25], v[176:179], v[206:209], v[22:25]
	v_mfma_f32_16x16x32_bf16 v[6:9], v[172:175], v[210:213], v[6:9]
	v_mfma_f32_16x16x32_bf16 v[6:9], v[176:179], v[214:217], v[6:9]
	s_setprio 0
	s_barrier
	s_add_i32 s84, s84, 2
	s_add_u32 s48, s48, 0x100
	s_addc_u32 s49, s49, 0
	s_add_u32 s53, s53, 0x100
	s_addc_u32 s69, s69, 0
	s_cmp_gt_u32 s84, 13
	s_cbranch_scc0 .LBB0_408
	s_and_b64 vcc, exec, s[64:65]
	s_cbranch_vccz .LBB0_411
	s_barrier
